# DN chunk-first step: operand reads reordered by first use and waited for one by one (counted lgkmcnt ladder) instead of a single lgkmcnt(0)
# baseline (speedup 1.0000x reference)
.LBB0_900:
	ds_read_b128 v[34:37], v1 offset:768
	ds_read_b128 v[2:5], v94 offset:256
	ds_read_b128 v[30:33], v94
	ds_read_b128 v[6:9], v94 offset:272
	ds_read_b128 v[26:29], v94 offset:16
	ds_read_b128 v[14:17], v94 offset:288
	ds_read_b128 v[22:25], v94 offset:32
	ds_read_b128 v[10:13], v94 offset:304
	ds_read_b128 v[18:21], v94 offset:48
	ds_read_b32 v73, v95 offset:512
	s_cmp_lg_u32 s4, 0
	s_cbranch_scc0 .Ldn_tok_ctx
	s_cmp_lg_u32 s4, 16
	s_cbranch_scc0 .Ldn_tok_lat
	s_lshl_b32 s2, s24, 5
	s_add_i32 s18, s18, s2

.LBB0_906:
	s_nop 0
	v_readfirstlane_b32 s100, v92
	v_readfirstlane_b32 s101, v93
	s_sub_u32 s100, s100, m0
	s_subb_u32 s101, s101, 0
	s_waitcnt lgkmcnt(9)
	v_pk_mul_f32 v[114:115], v[34:35], v[74:75] op_sel_hi:[0,1]
	v_pk_mul_f32 v[116:117], v[34:35], v[78:79] op_sel_hi:[0,1]
	s_waitcnt lgkmcnt(7)
	v_pk_fma_f32 v[106:107], v[114:115], v[2:3], 0 op_sel_hi:[1,1,0]
	v_pk_fma_f32 v[108:109], v[114:115], v[30:31], 0 op_sel_hi:[1,1,0]
	v_pk_mul_f32 v[118:119], v[34:35], v[80:81] op_sel_hi:[0,1]
	ds_read_b128 v[66:69], v94 offset:800
	v_pk_fma_f32 v[106:107], v[116:117], v[4:5], v[106:107]
	v_pk_fma_f32 v[108:109], v[116:117], v[32:33], v[108:109]
	v_pk_mul_f32 v[120:121], v[34:35], v[82:83] op_sel_hi:[0,1]
	ds_read_b128 v[62:65], v94 offset:816
	s_waitcnt lgkmcnt(7)
	v_pk_fma_f32 v[106:107], v[118:119], v[6:7], v[106:107]
	v_pk_fma_f32 v[108:109], v[118:119], v[26:27], v[108:109]
	v_pk_mul_f32 v[122:123], v[34:35], v[84:85] op_sel_hi:[0,1]
	ds_read_b128 v[58:61], v94 offset:832
	v_pk_fma_f32 v[106:107], v[120:121], v[8:9], v[106:107]
	v_pk_fma_f32 v[108:109], v[120:121], v[28:29], v[108:109]
	v_pk_mul_f32 v[124:125], v[34:35], v[86:87] op_sel_hi:[0,1]
	ds_read_b128 v[54:57], v94 offset:848
	s_waitcnt lgkmcnt(7)
	v_pk_fma_f32 v[106:107], v[122:123], v[14:15], v[106:107]
	v_pk_fma_f32 v[108:109], v[122:123], v[22:23], v[108:109]
	v_pk_mul_f32 v[126:127], v[34:35], v[88:89] op_sel_hi:[0,1]
	ds_read_b128 v[50:53], v94 offset:1056
	v_pk_fma_f32 v[106:107], v[124:125], v[16:17], v[106:107]
	v_pk_fma_f32 v[108:109], v[124:125], v[24:25], v[108:109]
	v_pk_mul_f32 v[128:129], v[34:35], v[90:91] op_sel_hi:[0,1]
	ds_read_b128 v[46:49], v94 offset:1072
	s_waitcnt lgkmcnt(7)
	v_pk_fma_f32 v[106:107], v[126:127], v[10:11], v[106:107]
	v_pk_fma_f32 v[108:109], v[126:127], v[18:19], v[108:109]
	ds_read_b128 v[42:45], v94 offset:1088
	v_pk_fma_f32 v[106:107], v[128:129], v[12:13], v[106:107]
	v_pk_fma_f32 v[108:109], v[128:129], v[20:21], v[108:109]
	ds_read_b128 v[38:41], v94 offset:1104
	v_add_f32_e32 v130, v106, v107
	v_add_f32_e32 v131, v108, v109
	ds_read_b32 v0, v95 offset:1312
	v_add_f32_dpp v130, v130, v130 quad_perm:[1,0,3,2] row_mask:0xf bank_mask:0xf bound_ctrl:1
	v_add_f32_dpp v131, v131, v131 quad_perm:[1,0,3,2] row_mask:0xf bank_mask:0xf bound_ctrl:1
	ds_read_b96 v[70:72], v1 offset:1568
	v_add_f32_dpp v130, v130, v130 quad_perm:[2,3,0,1] row_mask:0xf bank_mask:0xf bound_ctrl:1
	v_add_f32_dpp v131, v131, v131 quad_perm:[2,3,0,1] row_mask:0xf bank_mask:0xf bound_ctrl:1
	s_waitcnt lgkmcnt(10)
	v_sub_f32_e32 v130, v73, v130
	v_mul_f32_e32 v130, v35, v130
	v_fma_f32 v131, v36, v130, v131
	v_cvt_pk_bf16_f32 v132, v131, v131
	v_pk_fma_f32 v[74:75], v[2:3], v[130:131], v[114:115] op_sel_hi:[1,0,1]
	v_pk_fma_f32 v[78:79], v[4:5], v[130:131], v[116:117] op_sel_hi:[1,0,1]
	global_store_short v144, v132, s[100:101]
	v_pk_fma_f32 v[80:81], v[6:7], v[130:131], v[118:119] op_sel_hi:[1,0,1]
	v_pk_fma_f32 v[82:83], v[8:9], v[130:131], v[120:121] op_sel_hi:[1,0,1]
	v_pk_fma_f32 v[84:85], v[14:15], v[130:131], v[122:123] op_sel_hi:[1,0,1]
	v_pk_fma_f32 v[86:87], v[16:17], v[130:131], v[124:125] op_sel_hi:[1,0,1]
	v_pk_fma_f32 v[88:89], v[10:11], v[130:131], v[126:127] op_sel_hi:[1,0,1]
	v_pk_fma_f32 v[90:91], v[12:13], v[130:131], v[128:129] op_sel_hi:[1,0,1]
	s_waitcnt lgkmcnt(0)
	v_pk_mul_f32 v[114:115], v[70:71], v[74:75] op_sel_hi:[0,1]
	v_pk_mul_f32 v[116:117], v[70:71], v[78:79] op_sel_hi:[0,1]
	v_pk_fma_f32 v[110:111], v[114:115], v[50:51], 0 op_sel_hi:[1,1,0]
	v_pk_fma_f32 v[112:113], v[114:115], v[66:67], 0 op_sel_hi:[1,1,0]
	v_pk_mul_f32 v[118:119], v[70:71], v[80:81] op_sel_hi:[0,1]
	ds_read_b128 v[30:33], v94 offset:1600
	v_pk_fma_f32 v[110:111], v[116:117], v[52:53], v[110:111]
	v_pk_fma_f32 v[112:113], v[116:117], v[68:69], v[112:113]
	v_pk_mul_f32 v[120:121], v[70:71], v[82:83] op_sel_hi:[0,1]
	ds_read_b128 v[26:29], v94 offset:1616
	v_pk_fma_f32 v[110:111], v[118:119], v[46:47], v[110:111]
	v_pk_fma_f32 v[112:113], v[118:119], v[62:63], v[112:113]
	v_pk_mul_f32 v[122:123], v[70:71], v[84:85] op_sel_hi:[0,1]
	ds_read_b128 v[22:25], v94 offset:1632
	v_pk_fma_f32 v[110:111], v[120:121], v[48:49], v[110:111]
	v_pk_fma_f32 v[112:113], v[120:121], v[64:65], v[112:113]
	v_pk_mul_f32 v[124:125], v[70:71], v[86:87] op_sel_hi:[0,1]
	ds_read_b128 v[18:21], v94 offset:1648
	v_pk_fma_f32 v[110:111], v[122:123], v[42:43], v[110:111]
	v_pk_fma_f32 v[112:113], v[122:123], v[58:59], v[112:113]
	v_pk_mul_f32 v[126:127], v[70:71], v[88:89] op_sel_hi:[0,1]
	ds_read_b128 v[2:5], v94 offset:1856
	v_pk_fma_f32 v[110:111], v[124:125], v[44:45], v[110:111]
	v_pk_fma_f32 v[112:113], v[124:125], v[60:61], v[112:113]
	v_pk_mul_f32 v[128:129], v[70:71], v[90:91] op_sel_hi:[0,1]
	ds_read_b128 v[6:9], v94 offset:1872
	v_pk_fma_f32 v[110:111], v[126:127], v[38:39], v[110:111]
	v_pk_fma_f32 v[112:113], v[126:127], v[54:55], v[112:113]
	ds_read_b128 v[14:17], v94 offset:1888
	v_pk_fma_f32 v[110:111], v[128:129], v[40:41], v[110:111]
	v_pk_fma_f32 v[112:113], v[128:129], v[56:57], v[112:113]
	ds_read_b128 v[10:13], v94 offset:1904
	v_add_f32_e32 v134, v110, v111
	v_add_f32_e32 v135, v112, v113
	ds_read_b32 v73, v95 offset:2112
	v_add_f32_dpp v134, v134, v134 quad_perm:[1,0,3,2] row_mask:0xf bank_mask:0xf bound_ctrl:1
	v_add_f32_dpp v135, v135, v135 quad_perm:[1,0,3,2] row_mask:0xf bank_mask:0xf bound_ctrl:1
	ds_read_b96 v[34:36], v1 offset:2368
	v_add_f32_dpp v134, v134, v134 quad_perm:[2,3,0,1] row_mask:0xf bank_mask:0xf bound_ctrl:1
	v_add_f32_dpp v135, v135, v135 quad_perm:[2,3,0,1] row_mask:0xf bank_mask:0xf bound_ctrl:1
	v_sub_f32_e32 v134, v0, v134
	v_mul_f32_e32 v134, v71, v134
	v_fma_f32 v135, v72, v134, v135
	v_cvt_pk_bf16_f32 v133, v135, v135
	v_pk_fma_f32 v[74:75], v[50:51], v[134:135], v[114:115] op_sel_hi:[1,0,1]
	v_pk_fma_f32 v[78:79], v[52:53], v[134:135], v[116:117] op_sel_hi:[1,0,1]
	global_store_short v145, v133, s[100:101]
	v_pk_fma_f32 v[80:81], v[46:47], v[134:135], v[118:119] op_sel_hi:[1,0,1]
	v_pk_fma_f32 v[82:83], v[48:49], v[134:135], v[120:121] op_sel_hi:[1,0,1]
	v_pk_fma_f32 v[84:85], v[42:43], v[134:135], v[122:123] op_sel_hi:[1,0,1]
	v_pk_fma_f32 v[86:87], v[44:45], v[134:135], v[124:125] op_sel_hi:[1,0,1]
	v_pk_fma_f32 v[88:89], v[38:39], v[134:135], v[126:127] op_sel_hi:[1,0,1]
	v_pk_fma_f32 v[90:91], v[40:41], v[134:135], v[128:129] op_sel_hi:[1,0,1]
	s_waitcnt lgkmcnt(0)
	v_pk_mul_f32 v[114:115], v[34:35], v[74:75] op_sel_hi:[0,1]
	v_pk_mul_f32 v[116:117], v[34:35], v[78:79] op_sel_hi:[0,1]
	v_pk_fma_f32 v[106:107], v[114:115], v[2:3], 0 op_sel_hi:[1,1,0]
	v_pk_fma_f32 v[108:109], v[114:115], v[30:31], 0 op_sel_hi:[1,1,0]
	v_pk_mul_f32 v[118:119], v[34:35], v[80:81] op_sel_hi:[0,1]
	ds_read_b128 v[66:69], v94 offset:2400
	v_pk_fma_f32 v[106:107], v[116:117], v[4:5], v[106:107]
	v_pk_fma_f32 v[108:109], v[116:117], v[32:33], v[108:109]
	v_pk_mul_f32 v[120:121], v[34:35], v[82:83] op_sel_hi:[0,1]
	ds_read_b128 v[62:65], v94 offset:2416
	v_pk_fma_f32 v[106:107], v[118:119], v[6:7], v[106:107]
	v_pk_fma_f32 v[108:109], v[118:119], v[26:27], v[108:109]
	v_pk_mul_f32 v[122:123], v[34:35], v[84:85] op_sel_hi:[0,1]
	ds_read_b128 v[58:61], v94 offset:2432
	v_pk_fma_f32 v[106:107], v[120:121], v[8:9], v[106:107]
	v_pk_fma_f32 v[108:109], v[120:121], v[28:29], v[108:109]
	v_pk_mul_f32 v[124:125], v[34:35], v[86:87] op_sel_hi:[0,1]
	ds_read_b128 v[54:57], v94 offset:2448
	v_pk_fma_f32 v[106:107], v[122:123], v[14:15], v[106:107]
	v_pk_fma_f32 v[108:109], v[122:123], v[22:23], v[108:109]
	v_pk_mul_f32 v[126:127], v[34:35], v[88:89] op_sel_hi:[0,1]
	ds_read_b128 v[50:53], v94 offset:2656
	v_pk_fma_f32 v[106:107], v[124:125], v[16:17], v[106:107]
	v_pk_fma_f32 v[108:109], v[124:125], v[24:25], v[108:109]
	v_pk_mul_f32 v[128:129], v[34:35], v[90:91] op_sel_hi:[0,1]
	ds_read_b128 v[46:49], v94 offset:2672
	v_pk_fma_f32 v[106:107], v[126:127], v[10:11], v[106:107]
	v_pk_fma_f32 v[108:109], v[126:127], v[18:19], v[108:109]
	ds_read_b128 v[42:45], v94 offset:2688
	v_pk_fma_f32 v[106:107], v[128:129], v[12:13], v[106:107]
	v_pk_fma_f32 v[108:109], v[128:129], v[20:21], v[108:109]
	ds_read_b128 v[38:41], v94 offset:2704
	v_add_f32_e32 v130, v106, v107
	v_add_f32_e32 v131, v108, v109
	ds_read_b32 v0, v95 offset:2912
	v_add_f32_dpp v130, v130, v130 quad_perm:[1,0,3,2] row_mask:0xf bank_mask:0xf bound_ctrl:1
	v_add_f32_dpp v131, v131, v131 quad_perm:[1,0,3,2] row_mask:0xf bank_mask:0xf bound_ctrl:1
	ds_read_b96 v[70:72], v1 offset:3168
	v_add_f32_dpp v130, v130, v130 quad_perm:[2,3,0,1] row_mask:0xf bank_mask:0xf bound_ctrl:1
	v_add_f32_dpp v131, v131, v131 quad_perm:[2,3,0,1] row_mask:0xf bank_mask:0xf bound_ctrl:1
	v_sub_f32_e32 v130, v73, v130
	v_mul_f32_e32 v130, v35, v130
	v_fma_f32 v131, v36, v130, v131
	v_cvt_pk_bf16_f32 v132, v131, v131
	v_pk_fma_f32 v[74:75], v[2:3], v[130:131], v[114:115] op_sel_hi:[1,0,1]
	v_pk_fma_f32 v[78:79], v[4:5], v[130:131], v[116:117] op_sel_hi:[1,0,1]
	global_store_short v146, v132, s[100:101]
	v_pk_fma_f32 v[80:81], v[6:7], v[130:131], v[118:119] op_sel_hi:[1,0,1]
	v_pk_fma_f32 v[82:83], v[8:9], v[130:131], v[120:121] op_sel_hi:[1,0,1]
	v_pk_fma_f32 v[84:85], v[14:15], v[130:131], v[122:123] op_sel_hi:[1,0,1]
	v_pk_fma_f32 v[86:87], v[16:17], v[130:131], v[124:125] op_sel_hi:[1,0,1]
	v_pk_fma_f32 v[88:89], v[10:11], v[130:131], v[126:127] op_sel_hi:[1,0,1]
	v_pk_fma_f32 v[90:91], v[12:13], v[130:131], v[128:129] op_sel_hi:[1,0,1]
	s_waitcnt lgkmcnt(0)
	v_pk_mul_f32 v[114:115], v[70:71], v[74:75] op_sel_hi:[0,1]
	v_pk_mul_f32 v[116:117], v[70:71], v[78:79] op_sel_hi:[0,1]
	v_pk_fma_f32 v[110:111], v[114:115], v[50:51], 0 op_sel_hi:[1,1,0]
	v_pk_fma_f32 v[112:113], v[114:115], v[66:67], 0 op_sel_hi:[1,1,0]
	v_pk_mul_f32 v[118:119], v[70:71], v[80:81] op_sel_hi:[0,1]
	ds_read_b128 v[30:33], v94 offset:3200
	v_pk_fma_f32 v[110:111], v[116:117], v[52:53], v[110:111]
	v_pk_fma_f32 v[112:113], v[116:117], v[68:69], v[112:113]
	v_pk_mul_f32 v[120:121], v[70:71], v[82:83] op_sel_hi:[0,1]
	ds_read_b128 v[26:29], v94 offset:3216
	v_pk_fma_f32 v[110:111], v[118:119], v[46:47], v[110:111]
	v_pk_fma_f32 v[112:113], v[118:119], v[62:63], v[112:113]
	v_pk_mul_f32 v[122:123], v[70:71], v[84:85] op_sel_hi:[0,1]
	ds_read_b128 v[22:25], v94 offset:3232
	v_pk_fma_f32 v[110:111], v[120:121], v[48:49], v[110:111]
	v_pk_fma_f32 v[112:113], v[120:121], v[64:65], v[112:113]
	v_pk_mul_f32 v[124:125], v[70:71], v[86:87] op_sel_hi:[0,1]
	ds_read_b128 v[18:21], v94 offset:3248
	v_pk_fma_f32 v[110:111], v[122:123], v[42:43], v[110:111]
	v_pk_fma_f32 v[112:113], v[122:123], v[58:59], v[112:113]
	v_pk_mul_f32 v[126:127], v[70:71], v[88:89] op_sel_hi:[0,1]
	ds_read_b128 v[2:5], v94 offset:3456
	v_pk_fma_f32 v[110:111], v[124:125], v[44:45], v[110:111]
	v_pk_fma_f32 v[112:113], v[124:125], v[60:61], v[112:113]
	v_pk_mul_f32 v[128:129], v[70:71], v[90:91] op_sel_hi:[0,1]
	ds_read_b128 v[6:9], v94 offset:3472
	v_pk_fma_f32 v[110:111], v[126:127], v[38:39], v[110:111]
	v_pk_fma_f32 v[112:113], v[126:127], v[54:55], v[112:113]
	ds_read_b128 v[14:17], v94 offset:3488
	v_pk_fma_f32 v[110:111], v[128:129], v[40:41], v[110:111]
	v_pk_fma_f32 v[112:113], v[128:129], v[56:57], v[112:113]
	ds_read_b128 v[10:13], v94 offset:3504
	v_add_f32_e32 v134, v110, v111
	v_add_f32_e32 v135, v112, v113
	ds_read_b32 v73, v95 offset:3712
	v_add_f32_dpp v134, v134, v134 quad_perm:[1,0,3,2] row_mask:0xf bank_mask:0xf bound_ctrl:1
	v_add_f32_dpp v135, v135, v135 quad_perm:[1,0,3,2] row_mask:0xf bank_mask:0xf bound_ctrl:1
	ds_read_b96 v[34:36], v1 offset:3968
	v_add_f32_dpp v134, v134, v134 quad_perm:[2,3,0,1] row_mask:0xf bank_mask:0xf bound_ctrl:1
	v_add_f32_dpp v135, v135, v135 quad_perm:[2,3,0,1] row_mask:0xf bank_mask:0xf bound_ctrl:1
	v_sub_f32_e32 v134, v0, v134
	v_mul_f32_e32 v134, v71, v134
	v_fma_f32 v135, v72, v134, v135
	v_cvt_pk_bf16_f32 v133, v135, v135
	v_pk_fma_f32 v[74:75], v[50:51], v[134:135], v[114:115] op_sel_hi:[1,0,1]
	v_pk_fma_f32 v[78:79], v[52:53], v[134:135], v[116:117] op_sel_hi:[1,0,1]
	global_store_short v147, v133, s[100:101]
	v_pk_fma_f32 v[80:81], v[46:47], v[134:135], v[118:119] op_sel_hi:[1,0,1]
	v_pk_fma_f32 v[82:83], v[48:49], v[134:135], v[120:121] op_sel_hi:[1,0,1]
	v_pk_fma_f32 v[84:85], v[42:43], v[134:135], v[122:123] op_sel_hi:[1,0,1]
	v_pk_fma_f32 v[86:87], v[44:45], v[134:135], v[124:125] op_sel_hi:[1,0,1]
	v_pk_fma_f32 v[88:89], v[38:39], v[134:135], v[126:127] op_sel_hi:[1,0,1]
	v_pk_fma_f32 v[90:91], v[40:41], v[134:135], v[128:129] op_sel_hi:[1,0,1]
	s_waitcnt lgkmcnt(0)
	v_pk_mul_f32 v[114:115], v[34:35], v[74:75] op_sel_hi:[0,1]
	v_pk_mul_f32 v[116:117], v[34:35], v[78:79] op_sel_hi:[0,1]
	v_pk_fma_f32 v[106:107], v[114:115], v[2:3], 0 op_sel_hi:[1,1,0]
	v_pk_fma_f32 v[108:109], v[114:115], v[30:31], 0 op_sel_hi:[1,1,0]
	v_pk_mul_f32 v[118:119], v[34:35], v[80:81] op_sel_hi:[0,1]
	ds_read_b128 v[66:69], v94 offset:4000
	v_pk_fma_f32 v[106:107], v[116:117], v[4:5], v[106:107]
	v_pk_fma_f32 v[108:109], v[116:117], v[32:33], v[108:109]
	v_pk_mul_f32 v[120:121], v[34:35], v[82:83] op_sel_hi:[0,1]
	ds_read_b128 v[62:65], v94 offset:4016
	v_pk_fma_f32 v[106:107], v[118:119], v[6:7], v[106:107]
	v_pk_fma_f32 v[108:109], v[118:119], v[26:27], v[108:109]
	v_pk_mul_f32 v[122:123], v[34:35], v[84:85] op_sel_hi:[0,1]
	ds_read_b128 v[58:61], v94 offset:4032
	v_pk_fma_f32 v[106:107], v[120:121], v[8:9], v[106:107]
	v_pk_fma_f32 v[108:109], v[120:121], v[28:29], v[108:109]
	v_pk_mul_f32 v[124:125], v[34:35], v[86:87] op_sel_hi:[0,1]
	ds_read_b128 v[54:57], v94 offset:4048
	v_pk_fma_f32 v[106:107], v[122:123], v[14:15], v[106:107]
	v_pk_fma_f32 v[108:109], v[122:123], v[22:23], v[108:109]
	v_pk_mul_f32 v[126:127], v[34:35], v[88:89] op_sel_hi:[0,1]
	ds_read_b128 v[50:53], v94 offset:4256
	v_pk_fma_f32 v[106:107], v[124:125], v[16:17], v[106:107]
	v_pk_fma_f32 v[108:109], v[124:125], v[24:25], v[108:109]
	v_pk_mul_f32 v[128:129], v[34:35], v[90:91] op_sel_hi:[0,1]
	ds_read_b128 v[46:49], v94 offset:4272
	v_pk_fma_f32 v[106:107], v[126:127], v[10:11], v[106:107]
	v_pk_fma_f32 v[108:109], v[126:127], v[18:19], v[108:109]
	ds_read_b128 v[42:45], v94 offset:4288
	v_pk_fma_f32 v[106:107], v[128:129], v[12:13], v[106:107]
	v_pk_fma_f32 v[108:109], v[128:129], v[20:21], v[108:109]
	ds_read_b128 v[38:41], v94 offset:4304
	v_add_f32_e32 v130, v106, v107
	v_add_f32_e32 v131, v108, v109
	ds_read_b32 v0, v95 offset:4512
	v_add_f32_dpp v130, v130, v130 quad_perm:[1,0,3,2] row_mask:0xf bank_mask:0xf bound_ctrl:1
	v_add_f32_dpp v131, v131, v131 quad_perm:[1,0,3,2] row_mask:0xf bank_mask:0xf bound_ctrl:1
	ds_read_b96 v[70:72], v1 offset:4768
	v_add_f32_dpp v130, v130, v130 quad_perm:[2,3,0,1] row_mask:0xf bank_mask:0xf bound_ctrl:1
	v_add_f32_dpp v131, v131, v131 quad_perm:[2,3,0,1] row_mask:0xf bank_mask:0xf bound_ctrl:1
	v_sub_f32_e32 v130, v73, v130
	v_mul_f32_e32 v130, v35, v130
	v_fma_f32 v131, v36, v130, v131
	v_cvt_pk_bf16_f32 v132, v131, v131
	v_pk_fma_f32 v[74:75], v[2:3], v[130:131], v[114:115] op_sel_hi:[1,0,1]
	v_pk_fma_f32 v[78:79], v[4:5], v[130:131], v[116:117] op_sel_hi:[1,0,1]
	global_store_short v148, v132, s[100:101]
	v_pk_fma_f32 v[80:81], v[6:7], v[130:131], v[118:119] op_sel_hi:[1,0,1]
	v_pk_fma_f32 v[82:83], v[8:9], v[130:131], v[120:121] op_sel_hi:[1,0,1]
	v_pk_fma_f32 v[84:85], v[14:15], v[130:131], v[122:123] op_sel_hi:[1,0,1]
	v_pk_fma_f32 v[86:87], v[16:17], v[130:131], v[124:125] op_sel_hi:[1,0,1]
	v_pk_fma_f32 v[88:89], v[10:11], v[130:131], v[126:127] op_sel_hi:[1,0,1]
	v_pk_fma_f32 v[90:91], v[12:13], v[130:131], v[128:129] op_sel_hi:[1,0,1]
	s_waitcnt lgkmcnt(0)
	v_pk_mul_f32 v[114:115], v[70:71], v[74:75] op_sel_hi:[0,1]
	v_pk_mul_f32 v[116:117], v[70:71], v[78:79] op_sel_hi:[0,1]
	v_pk_fma_f32 v[110:111], v[114:115], v[50:51], 0 op_sel_hi:[1,1,0]
	v_pk_fma_f32 v[112:113], v[114:115], v[66:67], 0 op_sel_hi:[1,1,0]
	v_pk_mul_f32 v[118:119], v[70:71], v[80:81] op_sel_hi:[0,1]
	ds_read_b128 v[30:33], v94 offset:4800
	v_pk_fma_f32 v[110:111], v[116:117], v[52:53], v[110:111]
	v_pk_fma_f32 v[112:113], v[116:117], v[68:69], v[112:113]
	v_pk_mul_f32 v[120:121], v[70:71], v[82:83] op_sel_hi:[0,1]
	ds_read_b128 v[26:29], v94 offset:4816
	v_pk_fma_f32 v[110:111], v[118:119], v[46:47], v[110:111]
	v_pk_fma_f32 v[112:113], v[118:119], v[62:63], v[112:113]
	v_pk_mul_f32 v[122:123], v[70:71], v[84:85] op_sel_hi:[0,1]
	ds_read_b128 v[22:25], v94 offset:4832
	v_pk_fma_f32 v[110:111], v[120:121], v[48:49], v[110:111]
	v_pk_fma_f32 v[112:113], v[120:121], v[64:65], v[112:113]
	v_pk_mul_f32 v[124:125], v[70:71], v[86:87] op_sel_hi:[0,1]
	ds_read_b128 v[18:21], v94 offset:4848
	v_pk_fma_f32 v[110:111], v[122:123], v[42:43], v[110:111]
	v_pk_fma_f32 v[112:113], v[122:123], v[58:59], v[112:113]
	v_pk_mul_f32 v[126:127], v[70:71], v[88:89] op_sel_hi:[0,1]
	ds_read_b128 v[2:5], v94 offset:5056
	v_pk_fma_f32 v[110:111], v[124:125], v[44:45], v[110:111]
	v_pk_fma_f32 v[112:113], v[124:125], v[60:61], v[112:113]
	v_pk_mul_f32 v[128:129], v[70:71], v[90:91] op_sel_hi:[0,1]
	ds_read_b128 v[6:9], v94 offset:5072
	v_pk_fma_f32 v[110:111], v[126:127], v[38:39], v[110:111]
	v_pk_fma_f32 v[112:113], v[126:127], v[54:55], v[112:113]
	ds_read_b128 v[14:17], v94 offset:5088
	v_pk_fma_f32 v[110:111], v[128:129], v[40:41], v[110:111]
	v_pk_fma_f32 v[112:113], v[128:129], v[56:57], v[112:113]
	ds_read_b128 v[10:13], v94 offset:5104
	v_add_f32_e32 v134, v110, v111
	v_add_f32_e32 v135, v112, v113
	ds_read_b32 v73, v95 offset:5312
	v_add_f32_dpp v134, v134, v134 quad_perm:[1,0,3,2] row_mask:0xf bank_mask:0xf bound_ctrl:1
	v_add_f32_dpp v135, v135, v135 quad_perm:[1,0,3,2] row_mask:0xf bank_mask:0xf bound_ctrl:1
	ds_read_b96 v[34:36], v1 offset:5568
	v_add_f32_dpp v134, v134, v134 quad_perm:[2,3,0,1] row_mask:0xf bank_mask:0xf bound_ctrl:1
	v_add_f32_dpp v135, v135, v135 quad_perm:[2,3,0,1] row_mask:0xf bank_mask:0xf bound_ctrl:1
	v_sub_f32_e32 v134, v0, v134
	v_mul_f32_e32 v134, v71, v134
	v_fma_f32 v135, v72, v134, v135
	v_cvt_pk_bf16_f32 v133, v135, v135
	v_pk_fma_f32 v[74:75], v[50:51], v[134:135], v[114:115] op_sel_hi:[1,0,1]
	v_pk_fma_f32 v[78:79], v[52:53], v[134:135], v[116:117] op_sel_hi:[1,0,1]
	global_store_short v149, v133, s[100:101]
	v_pk_fma_f32 v[80:81], v[46:47], v[134:135], v[118:119] op_sel_hi:[1,0,1]
	v_pk_fma_f32 v[82:83], v[48:49], v[134:135], v[120:121] op_sel_hi:[1,0,1]
	v_pk_fma_f32 v[84:85], v[42:43], v[134:135], v[122:123] op_sel_hi:[1,0,1]
	v_pk_fma_f32 v[86:87], v[44:45], v[134:135], v[124:125] op_sel_hi:[1,0,1]
	v_pk_fma_f32 v[88:89], v[38:39], v[134:135], v[126:127] op_sel_hi:[1,0,1]
	v_pk_fma_f32 v[90:91], v[40:41], v[134:135], v[128:129] op_sel_hi:[1,0,1]
	s_waitcnt lgkmcnt(0)
	v_pk_mul_f32 v[114:115], v[34:35], v[74:75] op_sel_hi:[0,1]
	v_pk_mul_f32 v[116:117], v[34:35], v[78:79] op_sel_hi:[0,1]
	v_pk_fma_f32 v[106:107], v[114:115], v[2:3], 0 op_sel_hi:[1,1,0]
	v_pk_fma_f32 v[108:109], v[114:115], v[30:31], 0 op_sel_hi:[1,1,0]
	v_pk_mul_f32 v[118:119], v[34:35], v[80:81] op_sel_hi:[0,1]
	ds_read_b128 v[66:69], v94 offset:5600
	v_pk_fma_f32 v[106:107], v[116:117], v[4:5], v[106:107]
	v_pk_fma_f32 v[108:109], v[116:117], v[32:33], v[108:109]
	v_pk_mul_f32 v[120:121], v[34:35], v[82:83] op_sel_hi:[0,1]
	ds_read_b128 v[62:65], v94 offset:5616
	v_pk_fma_f32 v[106:107], v[118:119], v[6:7], v[106:107]
	v_pk_fma_f32 v[108:109], v[118:119], v[26:27], v[108:109]
	v_pk_mul_f32 v[122:123], v[34:35], v[84:85] op_sel_hi:[0,1]
	ds_read_b128 v[58:61], v94 offset:5632
	v_pk_fma_f32 v[106:107], v[120:121], v[8:9], v[106:107]
	v_pk_fma_f32 v[108:109], v[120:121], v[28:29], v[108:109]
	v_pk_mul_f32 v[124:125], v[34:35], v[86:87] op_sel_hi:[0,1]
	ds_read_b128 v[54:57], v94 offset:5648
	v_pk_fma_f32 v[106:107], v[122:123], v[14:15], v[106:107]
	v_pk_fma_f32 v[108:109], v[122:123], v[22:23], v[108:109]
	v_pk_mul_f32 v[126:127], v[34:35], v[88:89] op_sel_hi:[0,1]
	ds_read_b128 v[50:53], v94 offset:5856
	v_pk_fma_f32 v[106:107], v[124:125], v[16:17], v[106:107]
	v_pk_fma_f32 v[108:109], v[124:125], v[24:25], v[108:109]
	v_pk_mul_f32 v[128:129], v[34:35], v[90:91] op_sel_hi:[0,1]
	ds_read_b128 v[46:49], v94 offset:5872
	v_pk_fma_f32 v[106:107], v[126:127], v[10:11], v[106:107]
	v_pk_fma_f32 v[108:109], v[126:127], v[18:19], v[108:109]
	ds_read_b128 v[42:45], v94 offset:5888
	v_pk_fma_f32 v[106:107], v[128:129], v[12:13], v[106:107]
	v_pk_fma_f32 v[108:109], v[128:129], v[20:21], v[108:109]
	ds_read_b128 v[38:41], v94 offset:5904
	v_add_f32_e32 v130, v106, v107
	v_add_f32_e32 v131, v108, v109
	ds_read_b32 v0, v95 offset:6112
	v_add_f32_dpp v130, v130, v130 quad_perm:[1,0,3,2] row_mask:0xf bank_mask:0xf bound_ctrl:1
	v_add_f32_dpp v131, v131, v131 quad_perm:[1,0,3,2] row_mask:0xf bank_mask:0xf bound_ctrl:1
	ds_read_b96 v[70:72], v1 offset:6368
	v_add_f32_dpp v130, v130, v130 quad_perm:[2,3,0,1] row_mask:0xf bank_mask:0xf bound_ctrl:1
	v_add_f32_dpp v131, v131, v131 quad_perm:[2,3,0,1] row_mask:0xf bank_mask:0xf bound_ctrl:1
	v_sub_f32_e32 v130, v73, v130
	v_mul_f32_e32 v130, v35, v130
	v_fma_f32 v131, v36, v130, v131
	v_cvt_pk_bf16_f32 v132, v131, v131
	v_pk_fma_f32 v[74:75], v[2:3], v[130:131], v[114:115] op_sel_hi:[1,0,1]
	v_pk_fma_f32 v[78:79], v[4:5], v[130:131], v[116:117] op_sel_hi:[1,0,1]
	global_store_short v150, v132, s[100:101]
	v_pk_fma_f32 v[80:81], v[6:7], v[130:131], v[118:119] op_sel_hi:[1,0,1]
	v_pk_fma_f32 v[82:83], v[8:9], v[130:131], v[120:121] op_sel_hi:[1,0,1]
	v_pk_fma_f32 v[84:85], v[14:15], v[130:131], v[122:123] op_sel_hi:[1,0,1]
	v_pk_fma_f32 v[86:87], v[16:17], v[130:131], v[124:125] op_sel_hi:[1,0,1]
	v_pk_fma_f32 v[88:89], v[10:11], v[130:131], v[126:127] op_sel_hi:[1,0,1]
	v_pk_fma_f32 v[90:91], v[12:13], v[130:131], v[128:129] op_sel_hi:[1,0,1]
	s_waitcnt lgkmcnt(0)
	v_pk_mul_f32 v[114:115], v[70:71], v[74:75] op_sel_hi:[0,1]
	v_pk_mul_f32 v[116:117], v[70:71], v[78:79] op_sel_hi:[0,1]
	v_pk_fma_f32 v[110:111], v[114:115], v[50:51], 0 op_sel_hi:[1,1,0]
	v_pk_fma_f32 v[112:113], v[114:115], v[66:67], 0 op_sel_hi:[1,1,0]
	v_pk_mul_f32 v[118:119], v[70:71], v[80:81] op_sel_hi:[0,1]
	ds_read_b128 v[30:33], v94 offset:6400
	v_pk_fma_f32 v[110:111], v[116:117], v[52:53], v[110:111]
	v_pk_fma_f32 v[112:113], v[116:117], v[68:69], v[112:113]
	v_pk_mul_f32 v[120:121], v[70:71], v[82:83] op_sel_hi:[0,1]
	ds_read_b128 v[26:29], v94 offset:6416
	v_pk_fma_f32 v[110:111], v[118:119], v[46:47], v[110:111]
	v_pk_fma_f32 v[112:113], v[118:119], v[62:63], v[112:113]
	v_pk_mul_f32 v[122:123], v[70:71], v[84:85] op_sel_hi:[0,1]
	ds_read_b128 v[22:25], v94 offset:6432
	v_pk_fma_f32 v[110:111], v[120:121], v[48:49], v[110:111]
	v_pk_fma_f32 v[112:113], v[120:121], v[64:65], v[112:113]
	v_pk_mul_f32 v[124:125], v[70:71], v[86:87] op_sel_hi:[0,1]
	ds_read_b128 v[18:21], v94 offset:6448
	v_pk_fma_f32 v[110:111], v[122:123], v[42:43], v[110:111]
	v_pk_fma_f32 v[112:113], v[122:123], v[58:59], v[112:113]
	v_pk_mul_f32 v[126:127], v[70:71], v[88:89] op_sel_hi:[0,1]
	ds_read_b128 v[2:5], v94 offset:6656
	v_pk_fma_f32 v[110:111], v[124:125], v[44:45], v[110:111]
	v_pk_fma_f32 v[112:113], v[124:125], v[60:61], v[112:113]
	v_pk_mul_f32 v[128:129], v[70:71], v[90:91] op_sel_hi:[0,1]
	ds_read_b128 v[6:9], v94 offset:6672
	v_pk_fma_f32 v[110:111], v[126:127], v[38:39], v[110:111]
	v_pk_fma_f32 v[112:113], v[126:127], v[54:55], v[112:113]
	ds_read_b128 v[14:17], v94 offset:6688
	v_pk_fma_f32 v[110:111], v[128:129], v[40:41], v[110:111]
	v_pk_fma_f32 v[112:113], v[128:129], v[56:57], v[112:113]
	ds_read_b128 v[10:13], v94 offset:6704
	v_add_f32_e32 v134, v110, v111
	v_add_f32_e32 v135, v112, v113
	ds_read_b32 v73, v95 offset:6912
	v_add_f32_dpp v134, v134, v134 quad_perm:[1,0,3,2] row_mask:0xf bank_mask:0xf bound_ctrl:1
	v_add_f32_dpp v135, v135, v135 quad_perm:[1,0,3,2] row_mask:0xf bank_mask:0xf bound_ctrl:1
	ds_read_b96 v[34:36], v1 offset:7168
	v_add_f32_dpp v134, v134, v134 quad_perm:[2,3,0,1] row_mask:0xf bank_mask:0xf bound_ctrl:1
	v_add_f32_dpp v135, v135, v135 quad_perm:[2,3,0,1] row_mask:0xf bank_mask:0xf bound_ctrl:1
	v_sub_f32_e32 v134, v0, v134
	v_mul_f32_e32 v134, v71, v134
	v_fma_f32 v135, v72, v134, v135
	v_cvt_pk_bf16_f32 v133, v135, v135
	v_pk_fma_f32 v[74:75], v[50:51], v[134:135], v[114:115] op_sel_hi:[1,0,1]
	v_pk_fma_f32 v[78:79], v[52:53], v[134:135], v[116:117] op_sel_hi:[1,0,1]
	global_store_short v151, v133, s[100:101]
	v_pk_fma_f32 v[80:81], v[46:47], v[134:135], v[118:119] op_sel_hi:[1,0,1]
	v_pk_fma_f32 v[82:83], v[48:49], v[134:135], v[120:121] op_sel_hi:[1,0,1]
	v_pk_fma_f32 v[84:85], v[42:43], v[134:135], v[122:123] op_sel_hi:[1,0,1]
	v_pk_fma_f32 v[86:87], v[44:45], v[134:135], v[124:125] op_sel_hi:[1,0,1]
	v_pk_fma_f32 v[88:89], v[38:39], v[134:135], v[126:127] op_sel_hi:[1,0,1]
	v_pk_fma_f32 v[90:91], v[40:41], v[134:135], v[128:129] op_sel_hi:[1,0,1]
	s_waitcnt lgkmcnt(0)
	v_pk_mul_f32 v[114:115], v[34:35], v[74:75] op_sel_hi:[0,1]
	v_pk_mul_f32 v[116:117], v[34:35], v[78:79] op_sel_hi:[0,1]
	v_pk_fma_f32 v[106:107], v[114:115], v[2:3], 0 op_sel_hi:[1,1,0]
	v_pk_fma_f32 v[108:109], v[114:115], v[30:31], 0 op_sel_hi:[1,1,0]
	v_pk_mul_f32 v[118:119], v[34:35], v[80:81] op_sel_hi:[0,1]
	ds_read_b128 v[66:69], v94 offset:7200
	v_pk_fma_f32 v[106:107], v[116:117], v[4:5], v[106:107]
	v_pk_fma_f32 v[108:109], v[116:117], v[32:33], v[108:109]
	v_pk_mul_f32 v[120:121], v[34:35], v[82:83] op_sel_hi:[0,1]
	ds_read_b128 v[62:65], v94 offset:7216
	v_pk_fma_f32 v[106:107], v[118:119], v[6:7], v[106:107]
	v_pk_fma_f32 v[108:109], v[118:119], v[26:27], v[108:109]
	v_pk_mul_f32 v[122:123], v[34:35], v[84:85] op_sel_hi:[0,1]
	ds_read_b128 v[58:61], v94 offset:7232
	v_pk_fma_f32 v[106:107], v[120:121], v[8:9], v[106:107]
	v_pk_fma_f32 v[108:109], v[120:121], v[28:29], v[108:109]
	v_pk_mul_f32 v[124:125], v[34:35], v[86:87] op_sel_hi:[0,1]
	ds_read_b128 v[54:57], v94 offset:7248
	v_pk_fma_f32 v[106:107], v[122:123], v[14:15], v[106:107]
	v_pk_fma_f32 v[108:109], v[122:123], v[22:23], v[108:109]
	v_pk_mul_f32 v[126:127], v[34:35], v[88:89] op_sel_hi:[0,1]
	ds_read_b128 v[50:53], v94 offset:7456
	v_pk_fma_f32 v[106:107], v[124:125], v[16:17], v[106:107]
	v_pk_fma_f32 v[108:109], v[124:125], v[24:25], v[108:109]
	v_pk_mul_f32 v[128:129], v[34:35], v[90:91] op_sel_hi:[0,1]
	ds_read_b128 v[46:49], v94 offset:7472
	v_pk_fma_f32 v[106:107], v[126:127], v[10:11], v[106:107]
	v_pk_fma_f32 v[108:109], v[126:127], v[18:19], v[108:109]
	ds_read_b128 v[42:45], v94 offset:7488
	v_pk_fma_f32 v[106:107], v[128:129], v[12:13], v[106:107]
	v_pk_fma_f32 v[108:109], v[128:129], v[20:21], v[108:109]
	ds_read_b128 v[38:41], v94 offset:7504
	v_add_f32_e32 v130, v106, v107
	v_add_f32_e32 v131, v108, v109
	ds_read_b32 v0, v95 offset:7712
	v_add_f32_dpp v130, v130, v130 quad_perm:[1,0,3,2] row_mask:0xf bank_mask:0xf bound_ctrl:1
	v_add_f32_dpp v131, v131, v131 quad_perm:[1,0,3,2] row_mask:0xf bank_mask:0xf bound_ctrl:1
	ds_read_b96 v[70:72], v1 offset:7968
	v_add_f32_dpp v130, v130, v130 quad_perm:[2,3,0,1] row_mask:0xf bank_mask:0xf bound_ctrl:1
	v_add_f32_dpp v131, v131, v131 quad_perm:[2,3,0,1] row_mask:0xf bank_mask:0xf bound_ctrl:1
	v_sub_f32_e32 v130, v73, v130
	v_mul_f32_e32 v130, v35, v130
	v_fma_f32 v131, v36, v130, v131
	v_cvt_pk_bf16_f32 v132, v131, v131
	v_pk_fma_f32 v[74:75], v[2:3], v[130:131], v[114:115] op_sel_hi:[1,0,1]
	v_pk_fma_f32 v[78:79], v[4:5], v[130:131], v[116:117] op_sel_hi:[1,0,1]
	global_store_short v152, v132, s[100:101]
	v_pk_fma_f32 v[80:81], v[6:7], v[130:131], v[118:119] op_sel_hi:[1,0,1]
	v_pk_fma_f32 v[82:83], v[8:9], v[130:131], v[120:121] op_sel_hi:[1,0,1]
	v_pk_fma_f32 v[84:85], v[14:15], v[130:131], v[122:123] op_sel_hi:[1,0,1]
	v_pk_fma_f32 v[86:87], v[16:17], v[130:131], v[124:125] op_sel_hi:[1,0,1]
	v_pk_fma_f32 v[88:89], v[10:11], v[130:131], v[126:127] op_sel_hi:[1,0,1]
	v_pk_fma_f32 v[90:91], v[12:13], v[130:131], v[128:129] op_sel_hi:[1,0,1]
	s_waitcnt lgkmcnt(0)
	v_pk_mul_f32 v[114:115], v[70:71], v[74:75] op_sel_hi:[0,1]
	v_pk_mul_f32 v[116:117], v[70:71], v[78:79] op_sel_hi:[0,1]
	v_pk_fma_f32 v[110:111], v[114:115], v[50:51], 0 op_sel_hi:[1,1,0]
	v_pk_fma_f32 v[112:113], v[114:115], v[66:67], 0 op_sel_hi:[1,1,0]
	v_pk_mul_f32 v[118:119], v[70:71], v[80:81] op_sel_hi:[0,1]
	ds_read_b128 v[30:33], v94 offset:8000
	v_pk_fma_f32 v[110:111], v[116:117], v[52:53], v[110:111]
	v_pk_fma_f32 v[112:113], v[116:117], v[68:69], v[112:113]
	v_pk_mul_f32 v[120:121], v[70:71], v[82:83] op_sel_hi:[0,1]
	ds_read_b128 v[26:29], v94 offset:8016
	v_pk_fma_f32 v[110:111], v[118:119], v[46:47], v[110:111]
	v_pk_fma_f32 v[112:113], v[118:119], v[62:63], v[112:113]
	v_pk_mul_f32 v[122:123], v[70:71], v[84:85] op_sel_hi:[0,1]
	ds_read_b128 v[22:25], v94 offset:8032
	v_pk_fma_f32 v[110:111], v[120:121], v[48:49], v[110:111]
	v_pk_fma_f32 v[112:113], v[120:121], v[64:65], v[112:113]
	v_pk_mul_f32 v[124:125], v[70:71], v[86:87] op_sel_hi:[0,1]
	ds_read_b128 v[18:21], v94 offset:8048
	v_pk_fma_f32 v[110:111], v[122:123], v[42:43], v[110:111]
	v_pk_fma_f32 v[112:113], v[122:123], v[58:59], v[112:113]
	v_pk_mul_f32 v[126:127], v[70:71], v[88:89] op_sel_hi:[0,1]
	ds_read_b128 v[2:5], v94 offset:8256
	v_pk_fma_f32 v[110:111], v[124:125], v[44:45], v[110:111]
	v_pk_fma_f32 v[112:113], v[124:125], v[60:61], v[112:113]
	v_pk_mul_f32 v[128:129], v[70:71], v[90:91] op_sel_hi:[0,1]
	ds_read_b128 v[6:9], v94 offset:8272
	v_pk_fma_f32 v[110:111], v[126:127], v[38:39], v[110:111]
	v_pk_fma_f32 v[112:113], v[126:127], v[54:55], v[112:113]
	ds_read_b128 v[14:17], v94 offset:8288
	v_pk_fma_f32 v[110:111], v[128:129], v[40:41], v[110:111]
	v_pk_fma_f32 v[112:113], v[128:129], v[56:57], v[112:113]
	ds_read_b128 v[10:13], v94 offset:8304
	v_add_f32_e32 v134, v110, v111
	v_add_f32_e32 v135, v112, v113
	ds_read_b32 v73, v95 offset:8512
	v_add_f32_dpp v134, v134, v134 quad_perm:[1,0,3,2] row_mask:0xf bank_mask:0xf bound_ctrl:1
	v_add_f32_dpp v135, v135, v135 quad_perm:[1,0,3,2] row_mask:0xf bank_mask:0xf bound_ctrl:1
	ds_read_b96 v[34:36], v1 offset:8768
	v_add_f32_dpp v134, v134, v134 quad_perm:[2,3,0,1] row_mask:0xf bank_mask:0xf bound_ctrl:1
	v_add_f32_dpp v135, v135, v135 quad_perm:[2,3,0,1] row_mask:0xf bank_mask:0xf bound_ctrl:1
	v_sub_f32_e32 v134, v0, v134
	v_mul_f32_e32 v134, v71, v134
	v_fma_f32 v135, v72, v134, v135
	v_cvt_pk_bf16_f32 v133, v135, v135
	v_pk_fma_f32 v[74:75], v[50:51], v[134:135], v[114:115] op_sel_hi:[1,0,1]
	v_pk_fma_f32 v[78:79], v[52:53], v[134:135], v[116:117] op_sel_hi:[1,0,1]
	global_store_short v153, v133, s[100:101]
	v_pk_fma_f32 v[80:81], v[46:47], v[134:135], v[118:119] op_sel_hi:[1,0,1]
	v_pk_fma_f32 v[82:83], v[48:49], v[134:135], v[120:121] op_sel_hi:[1,0,1]
	v_pk_fma_f32 v[84:85], v[42:43], v[134:135], v[122:123] op_sel_hi:[1,0,1]
	v_pk_fma_f32 v[86:87], v[44:45], v[134:135], v[124:125] op_sel_hi:[1,0,1]
	v_pk_fma_f32 v[88:89], v[38:39], v[134:135], v[126:127] op_sel_hi:[1,0,1]
	v_pk_fma_f32 v[90:91], v[40:41], v[134:135], v[128:129] op_sel_hi:[1,0,1]
	s_waitcnt lgkmcnt(0)
	v_pk_mul_f32 v[114:115], v[34:35], v[74:75] op_sel_hi:[0,1]
	v_pk_mul_f32 v[116:117], v[34:35], v[78:79] op_sel_hi:[0,1]
	v_pk_fma_f32 v[106:107], v[114:115], v[2:3], 0 op_sel_hi:[1,1,0]
	v_pk_fma_f32 v[108:109], v[114:115], v[30:31], 0 op_sel_hi:[1,1,0]
	v_pk_mul_f32 v[118:119], v[34:35], v[80:81] op_sel_hi:[0,1]
	ds_read_b128 v[66:69], v94 offset:8800
	v_pk_fma_f32 v[106:107], v[116:117], v[4:5], v[106:107]
	v_pk_fma_f32 v[108:109], v[116:117], v[32:33], v[108:109]
	v_pk_mul_f32 v[120:121], v[34:35], v[82:83] op_sel_hi:[0,1]
	ds_read_b128 v[62:65], v94 offset:8816
	v_pk_fma_f32 v[106:107], v[118:119], v[6:7], v[106:107]
	v_pk_fma_f32 v[108:109], v[118:119], v[26:27], v[108:109]
	v_pk_mul_f32 v[122:123], v[34:35], v[84:85] op_sel_hi:[0,1]
	ds_read_b128 v[58:61], v94 offset:8832
	v_pk_fma_f32 v[106:107], v[120:121], v[8:9], v[106:107]
	v_pk_fma_f32 v[108:109], v[120:121], v[28:29], v[108:109]
	v_pk_mul_f32 v[124:125], v[34:35], v[86:87] op_sel_hi:[0,1]
	ds_read_b128 v[54:57], v94 offset:8848
	v_pk_fma_f32 v[106:107], v[122:123], v[14:15], v[106:107]
	v_pk_fma_f32 v[108:109], v[122:123], v[22:23], v[108:109]
	v_pk_mul_f32 v[126:127], v[34:35], v[88:89] op_sel_hi:[0,1]
	ds_read_b128 v[50:53], v94 offset:9056
	v_pk_fma_f32 v[106:107], v[124:125], v[16:17], v[106:107]
	v_pk_fma_f32 v[108:109], v[124:125], v[24:25], v[108:109]
	v_pk_mul_f32 v[128:129], v[34:35], v[90:91] op_sel_hi:[0,1]
	ds_read_b128 v[46:49], v94 offset:9072
	v_pk_fma_f32 v[106:107], v[126:127], v[10:11], v[106:107]
	v_pk_fma_f32 v[108:109], v[126:127], v[18:19], v[108:109]
	ds_read_b128 v[42:45], v94 offset:9088
	v_pk_fma_f32 v[106:107], v[128:129], v[12:13], v[106:107]
	v_pk_fma_f32 v[108:109], v[128:129], v[20:21], v[108:109]
	ds_read_b128 v[38:41], v94 offset:9104
	v_add_f32_e32 v130, v106, v107
	v_add_f32_e32 v131, v108, v109
	ds_read_b32 v0, v95 offset:9312
	v_add_f32_dpp v130, v130, v130 quad_perm:[1,0,3,2] row_mask:0xf bank_mask:0xf bound_ctrl:1
	v_add_f32_dpp v131, v131, v131 quad_perm:[1,0,3,2] row_mask:0xf bank_mask:0xf bound_ctrl:1
	ds_read_b96 v[70:72], v1 offset:9568
	v_add_f32_dpp v130, v130, v130 quad_perm:[2,3,0,1] row_mask:0xf bank_mask:0xf bound_ctrl:1
	v_add_f32_dpp v131, v131, v131 quad_perm:[2,3,0,1] row_mask:0xf bank_mask:0xf bound_ctrl:1
	v_sub_f32_e32 v130, v73, v130
	v_mul_f32_e32 v130, v35, v130
	v_fma_f32 v131, v36, v130, v131
	v_cvt_pk_bf16_f32 v132, v131, v131
	v_pk_fma_f32 v[74:75], v[2:3], v[130:131], v[114:115] op_sel_hi:[1,0,1]
	v_pk_fma_f32 v[78:79], v[4:5], v[130:131], v[116:117] op_sel_hi:[1,0,1]
	global_store_short v154, v132, s[100:101]
	v_pk_fma_f32 v[80:81], v[6:7], v[130:131], v[118:119] op_sel_hi:[1,0,1]
	v_pk_fma_f32 v[82:83], v[8:9], v[130:131], v[120:121] op_sel_hi:[1,0,1]
	v_pk_fma_f32 v[84:85], v[14:15], v[130:131], v[122:123] op_sel_hi:[1,0,1]
	v_pk_fma_f32 v[86:87], v[16:17], v[130:131], v[124:125] op_sel_hi:[1,0,1]
	v_pk_fma_f32 v[88:89], v[10:11], v[130:131], v[126:127] op_sel_hi:[1,0,1]
	v_pk_fma_f32 v[90:91], v[12:13], v[130:131], v[128:129] op_sel_hi:[1,0,1]
	s_waitcnt lgkmcnt(0)
	v_pk_mul_f32 v[114:115], v[70:71], v[74:75] op_sel_hi:[0,1]
	v_pk_mul_f32 v[116:117], v[70:71], v[78:79] op_sel_hi:[0,1]
	v_pk_fma_f32 v[110:111], v[114:115], v[50:51], 0 op_sel_hi:[1,1,0]
	v_pk_fma_f32 v[112:113], v[114:115], v[66:67], 0 op_sel_hi:[1,1,0]
	v_pk_mul_f32 v[118:119], v[70:71], v[80:81] op_sel_hi:[0,1]
	ds_read_b128 v[30:33], v94 offset:9600
	v_pk_fma_f32 v[110:111], v[116:117], v[52:53], v[110:111]
	v_pk_fma_f32 v[112:113], v[116:117], v[68:69], v[112:113]
	v_pk_mul_f32 v[120:121], v[70:71], v[82:83] op_sel_hi:[0,1]
	ds_read_b128 v[26:29], v94 offset:9616
	v_pk_fma_f32 v[110:111], v[118:119], v[46:47], v[110:111]
	v_pk_fma_f32 v[112:113], v[118:119], v[62:63], v[112:113]
	v_pk_mul_f32 v[122:123], v[70:71], v[84:85] op_sel_hi:[0,1]
	ds_read_b128 v[22:25], v94 offset:9632
	v_pk_fma_f32 v[110:111], v[120:121], v[48:49], v[110:111]
	v_pk_fma_f32 v[112:113], v[120:121], v[64:65], v[112:113]
	v_pk_mul_f32 v[124:125], v[70:71], v[86:87] op_sel_hi:[0,1]
	ds_read_b128 v[18:21], v94 offset:9648
	v_pk_fma_f32 v[110:111], v[122:123], v[42:43], v[110:111]
	v_pk_fma_f32 v[112:113], v[122:123], v[58:59], v[112:113]
	v_pk_mul_f32 v[126:127], v[70:71], v[88:89] op_sel_hi:[0,1]
	ds_read_b128 v[2:5], v94 offset:9856
	v_pk_fma_f32 v[110:111], v[124:125], v[44:45], v[110:111]
	v_pk_fma_f32 v[112:113], v[124:125], v[60:61], v[112:113]
	v_pk_mul_f32 v[128:129], v[70:71], v[90:91] op_sel_hi:[0,1]
	ds_read_b128 v[6:9], v94 offset:9872
	v_pk_fma_f32 v[110:111], v[126:127], v[38:39], v[110:111]
	v_pk_fma_f32 v[112:113], v[126:127], v[54:55], v[112:113]
	ds_read_b128 v[14:17], v94 offset:9888
	v_pk_fma_f32 v[110:111], v[128:129], v[40:41], v[110:111]
	v_pk_fma_f32 v[112:113], v[128:129], v[56:57], v[112:113]
	ds_read_b128 v[10:13], v94 offset:9904
	v_add_f32_e32 v134, v110, v111
	v_add_f32_e32 v135, v112, v113
	ds_read_b32 v73, v95 offset:10112
	v_add_f32_dpp v134, v134, v134 quad_perm:[1,0,3,2] row_mask:0xf bank_mask:0xf bound_ctrl:1
	v_add_f32_dpp v135, v135, v135 quad_perm:[1,0,3,2] row_mask:0xf bank_mask:0xf bound_ctrl:1
	ds_read_b96 v[34:36], v1 offset:10368
	v_add_f32_dpp v134, v134, v134 quad_perm:[2,3,0,1] row_mask:0xf bank_mask:0xf bound_ctrl:1
	v_add_f32_dpp v135, v135, v135 quad_perm:[2,3,0,1] row_mask:0xf bank_mask:0xf bound_ctrl:1
	v_sub_f32_e32 v134, v0, v134
	v_mul_f32_e32 v134, v71, v134
	v_fma_f32 v135, v72, v134, v135
	v_cvt_pk_bf16_f32 v133, v135, v135
	v_pk_fma_f32 v[74:75], v[50:51], v[134:135], v[114:115] op_sel_hi:[1,0,1]
	v_pk_fma_f32 v[78:79], v[52:53], v[134:135], v[116:117] op_sel_hi:[1,0,1]
	global_store_short v155, v133, s[100:101]
	v_pk_fma_f32 v[80:81], v[46:47], v[134:135], v[118:119] op_sel_hi:[1,0,1]
	v_pk_fma_f32 v[82:83], v[48:49], v[134:135], v[120:121] op_sel_hi:[1,0,1]
	v_pk_fma_f32 v[84:85], v[42:43], v[134:135], v[122:123] op_sel_hi:[1,0,1]
	v_pk_fma_f32 v[86:87], v[44:45], v[134:135], v[124:125] op_sel_hi:[1,0,1]
	v_pk_fma_f32 v[88:89], v[38:39], v[134:135], v[126:127] op_sel_hi:[1,0,1]
	v_pk_fma_f32 v[90:91], v[40:41], v[134:135], v[128:129] op_sel_hi:[1,0,1]
	s_waitcnt lgkmcnt(0)
	v_pk_mul_f32 v[114:115], v[34:35], v[74:75] op_sel_hi:[0,1]
	v_pk_mul_f32 v[116:117], v[34:35], v[78:79] op_sel_hi:[0,1]
	v_pk_fma_f32 v[106:107], v[114:115], v[2:3], 0 op_sel_hi:[1,1,0]
	v_pk_fma_f32 v[108:109], v[114:115], v[30:31], 0 op_sel_hi:[1,1,0]
	v_pk_mul_f32 v[118:119], v[34:35], v[80:81] op_sel_hi:[0,1]
	ds_read_b128 v[66:69], v94 offset:10400
	v_pk_fma_f32 v[106:107], v[116:117], v[4:5], v[106:107]
	v_pk_fma_f32 v[108:109], v[116:117], v[32:33], v[108:109]
	v_pk_mul_f32 v[120:121], v[34:35], v[82:83] op_sel_hi:[0,1]
	ds_read_b128 v[62:65], v94 offset:10416
	v_pk_fma_f32 v[106:107], v[118:119], v[6:7], v[106:107]
	v_pk_fma_f32 v[108:109], v[118:119], v[26:27], v[108:109]
	v_pk_mul_f32 v[122:123], v[34:35], v[84:85] op_sel_hi:[0,1]
	ds_read_b128 v[58:61], v94 offset:10432
	v_pk_fma_f32 v[106:107], v[120:121], v[8:9], v[106:107]
	v_pk_fma_f32 v[108:109], v[120:121], v[28:29], v[108:109]
	v_pk_mul_f32 v[124:125], v[34:35], v[86:87] op_sel_hi:[0,1]
	ds_read_b128 v[54:57], v94 offset:10448
	v_pk_fma_f32 v[106:107], v[122:123], v[14:15], v[106:107]
	v_pk_fma_f32 v[108:109], v[122:123], v[22:23], v[108:109]
	v_pk_mul_f32 v[126:127], v[34:35], v[88:89] op_sel_hi:[0,1]
	ds_read_b128 v[50:53], v94 offset:10656
	v_pk_fma_f32 v[106:107], v[124:125], v[16:17], v[106:107]
	v_pk_fma_f32 v[108:109], v[124:125], v[24:25], v[108:109]
	v_pk_mul_f32 v[128:129], v[34:35], v[90:91] op_sel_hi:[0,1]
	ds_read_b128 v[46:49], v94 offset:10672
	v_pk_fma_f32 v[106:107], v[126:127], v[10:11], v[106:107]
	v_pk_fma_f32 v[108:109], v[126:127], v[18:19], v[108:109]
	ds_read_b128 v[42:45], v94 offset:10688
	v_pk_fma_f32 v[106:107], v[128:129], v[12:13], v[106:107]
	v_pk_fma_f32 v[108:109], v[128:129], v[20:21], v[108:109]
	ds_read_b128 v[38:41], v94 offset:10704
	v_add_f32_e32 v130, v106, v107
	v_add_f32_e32 v131, v108, v109
	ds_read_b32 v0, v95 offset:10912
	v_add_f32_dpp v130, v130, v130 quad_perm:[1,0,3,2] row_mask:0xf bank_mask:0xf bound_ctrl:1
	v_add_f32_dpp v131, v131, v131 quad_perm:[1,0,3,2] row_mask:0xf bank_mask:0xf bound_ctrl:1
	ds_read_b96 v[70:72], v1 offset:11168
	v_add_f32_dpp v130, v130, v130 quad_perm:[2,3,0,1] row_mask:0xf bank_mask:0xf bound_ctrl:1
	v_add_f32_dpp v131, v131, v131 quad_perm:[2,3,0,1] row_mask:0xf bank_mask:0xf bound_ctrl:1
	v_sub_f32_e32 v130, v73, v130
	v_mul_f32_e32 v130, v35, v130
	v_fma_f32 v131, v36, v130, v131
	v_cvt_pk_bf16_f32 v132, v131, v131
	v_pk_fma_f32 v[74:75], v[2:3], v[130:131], v[114:115] op_sel_hi:[1,0,1]
	v_pk_fma_f32 v[78:79], v[4:5], v[130:131], v[116:117] op_sel_hi:[1,0,1]
	global_store_short v156, v132, s[100:101]
	v_pk_fma_f32 v[80:81], v[6:7], v[130:131], v[118:119] op_sel_hi:[1,0,1]
	v_pk_fma_f32 v[82:83], v[8:9], v[130:131], v[120:121] op_sel_hi:[1,0,1]
	v_pk_fma_f32 v[84:85], v[14:15], v[130:131], v[122:123] op_sel_hi:[1,0,1]
	v_pk_fma_f32 v[86:87], v[16:17], v[130:131], v[124:125] op_sel_hi:[1,0,1]
	v_pk_fma_f32 v[88:89], v[10:11], v[130:131], v[126:127] op_sel_hi:[1,0,1]
	v_pk_fma_f32 v[90:91], v[12:13], v[130:131], v[128:129] op_sel_hi:[1,0,1]
	s_waitcnt lgkmcnt(0)
	v_pk_mul_f32 v[114:115], v[70:71], v[74:75] op_sel_hi:[0,1]
	v_pk_mul_f32 v[116:117], v[70:71], v[78:79] op_sel_hi:[0,1]
	v_pk_fma_f32 v[110:111], v[114:115], v[50:51], 0 op_sel_hi:[1,1,0]
	v_pk_fma_f32 v[112:113], v[114:115], v[66:67], 0 op_sel_hi:[1,1,0]
	v_pk_mul_f32 v[118:119], v[70:71], v[80:81] op_sel_hi:[0,1]
	ds_read_b128 v[30:33], v94 offset:11200
	v_pk_fma_f32 v[110:111], v[116:117], v[52:53], v[110:111]
	v_pk_fma_f32 v[112:113], v[116:117], v[68:69], v[112:113]
	v_pk_mul_f32 v[120:121], v[70:71], v[82:83] op_sel_hi:[0,1]
	ds_read_b128 v[26:29], v94 offset:11216
	v_pk_fma_f32 v[110:111], v[118:119], v[46:47], v[110:111]
	v_pk_fma_f32 v[112:113], v[118:119], v[62:63], v[112:113]
	v_pk_mul_f32 v[122:123], v[70:71], v[84:85] op_sel_hi:[0,1]
	ds_read_b128 v[22:25], v94 offset:11232
	v_pk_fma_f32 v[110:111], v[120:121], v[48:49], v[110:111]
	v_pk_fma_f32 v[112:113], v[120:121], v[64:65], v[112:113]
	v_pk_mul_f32 v[124:125], v[70:71], v[86:87] op_sel_hi:[0,1]
	ds_read_b128 v[18:21], v94 offset:11248
	v_pk_fma_f32 v[110:111], v[122:123], v[42:43], v[110:111]
	v_pk_fma_f32 v[112:113], v[122:123], v[58:59], v[112:113]
	v_pk_mul_f32 v[126:127], v[70:71], v[88:89] op_sel_hi:[0,1]
	ds_read_b128 v[2:5], v94 offset:11456
	v_pk_fma_f32 v[110:111], v[124:125], v[44:45], v[110:111]
	v_pk_fma_f32 v[112:113], v[124:125], v[60:61], v[112:113]
	v_pk_mul_f32 v[128:129], v[70:71], v[90:91] op_sel_hi:[0,1]
	ds_read_b128 v[6:9], v94 offset:11472
	v_pk_fma_f32 v[110:111], v[126:127], v[38:39], v[110:111]
	v_pk_fma_f32 v[112:113], v[126:127], v[54:55], v[112:113]
	ds_read_b128 v[14:17], v94 offset:11488
	v_pk_fma_f32 v[110:111], v[128:129], v[40:41], v[110:111]
	v_pk_fma_f32 v[112:113], v[128:129], v[56:57], v[112:113]
	ds_read_b128 v[10:13], v94 offset:11504
	v_add_f32_e32 v134, v110, v111
	v_add_f32_e32 v135, v112, v113
	ds_read_b32 v73, v95 offset:11712
	v_add_f32_dpp v134, v134, v134 quad_perm:[1,0,3,2] row_mask:0xf bank_mask:0xf bound_ctrl:1
	v_add_f32_dpp v135, v135, v135 quad_perm:[1,0,3,2] row_mask:0xf bank_mask:0xf bound_ctrl:1
	ds_read_b96 v[34:36], v1 offset:11968
	v_add_f32_dpp v134, v134, v134 quad_perm:[2,3,0,1] row_mask:0xf bank_mask:0xf bound_ctrl:1
	v_add_f32_dpp v135, v135, v135 quad_perm:[2,3,0,1] row_mask:0xf bank_mask:0xf bound_ctrl:1
	v_sub_f32_e32 v134, v0, v134
	v_mul_f32_e32 v134, v71, v134
	v_fma_f32 v135, v72, v134, v135
	v_cvt_pk_bf16_f32 v133, v135, v135
	v_pk_fma_f32 v[74:75], v[50:51], v[134:135], v[114:115] op_sel_hi:[1,0,1]
	v_pk_fma_f32 v[78:79], v[52:53], v[134:135], v[116:117] op_sel_hi:[1,0,1]
	global_store_short v157, v133, s[100:101]
	v_pk_fma_f32 v[80:81], v[46:47], v[134:135], v[118:119] op_sel_hi:[1,0,1]
	v_pk_fma_f32 v[82:83], v[48:49], v[134:135], v[120:121] op_sel_hi:[1,0,1]
	v_pk_fma_f32 v[84:85], v[42:43], v[134:135], v[122:123] op_sel_hi:[1,0,1]
	v_pk_fma_f32 v[86:87], v[44:45], v[134:135], v[124:125] op_sel_hi:[1,0,1]
	v_pk_fma_f32 v[88:89], v[38:39], v[134:135], v[126:127] op_sel_hi:[1,0,1]
	v_pk_fma_f32 v[90:91], v[40:41], v[134:135], v[128:129] op_sel_hi:[1,0,1]
	s_waitcnt lgkmcnt(0)
	v_pk_mul_f32 v[114:115], v[34:35], v[74:75] op_sel_hi:[0,1]
	v_pk_mul_f32 v[116:117], v[34:35], v[78:79] op_sel_hi:[0,1]
	v_pk_fma_f32 v[106:107], v[114:115], v[2:3], 0 op_sel_hi:[1,1,0]
	v_pk_fma_f32 v[108:109], v[114:115], v[30:31], 0 op_sel_hi:[1,1,0]
	v_pk_mul_f32 v[118:119], v[34:35], v[80:81] op_sel_hi:[0,1]
	ds_read_b128 v[66:69], v94 offset:12000
	v_pk_fma_f32 v[106:107], v[116:117], v[4:5], v[106:107]
	v_pk_fma_f32 v[108:109], v[116:117], v[32:33], v[108:109]
	v_pk_mul_f32 v[120:121], v[34:35], v[82:83] op_sel_hi:[0,1]
	ds_read_b128 v[62:65], v94 offset:12016
	v_pk_fma_f32 v[106:107], v[118:119], v[6:7], v[106:107]
	v_pk_fma_f32 v[108:109], v[118:119], v[26:27], v[108:109]
	v_pk_mul_f32 v[122:123], v[34:35], v[84:85] op_sel_hi:[0,1]
	ds_read_b128 v[58:61], v94 offset:12032
	v_pk_fma_f32 v[106:107], v[120:121], v[8:9], v[106:107]
	v_pk_fma_f32 v[108:109], v[120:121], v[28:29], v[108:109]
	v_pk_mul_f32 v[124:125], v[34:35], v[86:87] op_sel_hi:[0,1]
	ds_read_b128 v[54:57], v94 offset:12048
	v_pk_fma_f32 v[106:107], v[122:123], v[14:15], v[106:107]
	v_pk_fma_f32 v[108:109], v[122:123], v[22:23], v[108:109]
	v_pk_mul_f32 v[126:127], v[34:35], v[88:89] op_sel_hi:[0,1]
	ds_read_b128 v[50:53], v94 offset:12256
	v_pk_fma_f32 v[106:107], v[124:125], v[16:17], v[106:107]
	v_pk_fma_f32 v[108:109], v[124:125], v[24:25], v[108:109]
	v_pk_mul_f32 v[128:129], v[34:35], v[90:91] op_sel_hi:[0,1]
	ds_read_b128 v[46:49], v94 offset:12272
	v_pk_fma_f32 v[106:107], v[126:127], v[10:11], v[106:107]
	v_pk_fma_f32 v[108:109], v[126:127], v[18:19], v[108:109]
	ds_read_b128 v[42:45], v94 offset:12288
	v_pk_fma_f32 v[106:107], v[128:129], v[12:13], v[106:107]
	v_pk_fma_f32 v[108:109], v[128:129], v[20:21], v[108:109]
	ds_read_b128 v[38:41], v94 offset:12304
	v_add_f32_e32 v130, v106, v107
	v_add_f32_e32 v131, v108, v109
	ds_read_b32 v0, v95 offset:12512
	v_add_f32_dpp v130, v130, v130 quad_perm:[1,0,3,2] row_mask:0xf bank_mask:0xf bound_ctrl:1
	v_add_f32_dpp v131, v131, v131 quad_perm:[1,0,3,2] row_mask:0xf bank_mask:0xf bound_ctrl:1
	ds_read_b96 v[70:72], v1 offset:12768
	v_add_f32_dpp v130, v130, v130 quad_perm:[2,3,0,1] row_mask:0xf bank_mask:0xf bound_ctrl:1
	v_add_f32_dpp v131, v131, v131 quad_perm:[2,3,0,1] row_mask:0xf bank_mask:0xf bound_ctrl:1
	v_sub_f32_e32 v130, v73, v130
	v_mul_f32_e32 v130, v35, v130
	v_fma_f32 v131, v36, v130, v131
	v_cvt_pk_bf16_f32 v132, v131, v131
	v_pk_fma_f32 v[74:75], v[2:3], v[130:131], v[114:115] op_sel_hi:[1,0,1]
	v_pk_fma_f32 v[78:79], v[4:5], v[130:131], v[116:117] op_sel_hi:[1,0,1]
	global_store_short v158, v132, s[100:101]
	v_pk_fma_f32 v[80:81], v[6:7], v[130:131], v[118:119] op_sel_hi:[1,0,1]
	v_pk_fma_f32 v[82:83], v[8:9], v[130:131], v[120:121] op_sel_hi:[1,0,1]
	v_pk_fma_f32 v[84:85], v[14:15], v[130:131], v[122:123] op_sel_hi:[1,0,1]
	v_pk_fma_f32 v[86:87], v[16:17], v[130:131], v[124:125] op_sel_hi:[1,0,1]
	v_pk_fma_f32 v[88:89], v[10:11], v[130:131], v[126:127] op_sel_hi:[1,0,1]
	v_pk_fma_f32 v[90:91], v[12:13], v[130:131], v[128:129] op_sel_hi:[1,0,1]
	s_waitcnt lgkmcnt(0)
	v_pk_mul_f32 v[114:115], v[70:71], v[74:75] op_sel_hi:[0,1]
	v_pk_mul_f32 v[116:117], v[70:71], v[78:79] op_sel_hi:[0,1]
	v_pk_fma_f32 v[110:111], v[114:115], v[50:51], 0 op_sel_hi:[1,1,0]
	v_pk_fma_f32 v[112:113], v[114:115], v[66:67], 0 op_sel_hi:[1,1,0]
	v_pk_mul_f32 v[118:119], v[70:71], v[80:81] op_sel_hi:[0,1]
	v_pk_fma_f32 v[110:111], v[116:117], v[52:53], v[110:111]
	v_pk_fma_f32 v[112:113], v[116:117], v[68:69], v[112:113]
	v_pk_mul_f32 v[120:121], v[70:71], v[82:83] op_sel_hi:[0,1]
	v_pk_fma_f32 v[110:111], v[118:119], v[46:47], v[110:111]
	v_pk_fma_f32 v[112:113], v[118:119], v[62:63], v[112:113]
	v_pk_mul_f32 v[122:123], v[70:71], v[84:85] op_sel_hi:[0,1]
	v_pk_fma_f32 v[110:111], v[120:121], v[48:49], v[110:111]
	v_pk_fma_f32 v[112:113], v[120:121], v[64:65], v[112:113]
	v_pk_mul_f32 v[124:125], v[70:71], v[86:87] op_sel_hi:[0,1]
	v_pk_fma_f32 v[110:111], v[122:123], v[42:43], v[110:111]
	v_pk_fma_f32 v[112:113], v[122:123], v[58:59], v[112:113]
	v_pk_mul_f32 v[126:127], v[70:71], v[88:89] op_sel_hi:[0,1]
	v_pk_fma_f32 v[110:111], v[124:125], v[44:45], v[110:111]
	v_pk_fma_f32 v[112:113], v[124:125], v[60:61], v[112:113]
	v_pk_mul_f32 v[128:129], v[70:71], v[90:91] op_sel_hi:[0,1]
	v_pk_fma_f32 v[110:111], v[126:127], v[38:39], v[110:111]
	v_pk_fma_f32 v[112:113], v[126:127], v[54:55], v[112:113]
	v_pk_fma_f32 v[110:111], v[128:129], v[40:41], v[110:111]
	v_pk_fma_f32 v[112:113], v[128:129], v[56:57], v[112:113]
	v_add_f32_e32 v134, v110, v111
	v_add_f32_e32 v135, v112, v113
	s_nop 0
	v_add_f32_dpp v134, v134, v134 quad_perm:[1,0,3,2] row_mask:0xf bank_mask:0xf bound_ctrl:1
	v_add_f32_dpp v135, v135, v135 quad_perm:[1,0,3,2] row_mask:0xf bank_mask:0xf bound_ctrl:1
	s_nop 0
	v_add_f32_dpp v134, v134, v134 quad_perm:[2,3,0,1] row_mask:0xf bank_mask:0xf bound_ctrl:1
	v_add_f32_dpp v135, v135, v135 quad_perm:[2,3,0,1] row_mask:0xf bank_mask:0xf bound_ctrl:1
	v_sub_f32_e32 v134, v0, v134
	v_mul_f32_e32 v134, v71, v134
	v_fma_f32 v135, v72, v134, v135
	v_cvt_pk_bf16_f32 v133, v135, v135
	v_pk_fma_f32 v[74:75], v[50:51], v[134:135], v[114:115] op_sel_hi:[1,0,1]
	v_pk_fma_f32 v[78:79], v[52:53], v[134:135], v[116:117] op_sel_hi:[1,0,1]
	global_store_short v159, v133, s[100:101]
	v_pk_fma_f32 v[80:81], v[46:47], v[134:135], v[118:119] op_sel_hi:[1,0,1]
	v_pk_fma_f32 v[82:83], v[48:49], v[134:135], v[120:121] op_sel_hi:[1,0,1]
	v_pk_fma_f32 v[84:85], v[42:43], v[134:135], v[122:123] op_sel_hi:[1,0,1]
	v_pk_fma_f32 v[86:87], v[44:45], v[134:135], v[124:125] op_sel_hi:[1,0,1]
	v_pk_fma_f32 v[88:89], v[38:39], v[134:135], v[126:127] op_sel_hi:[1,0,1]
	v_pk_fma_f32 v[90:91], v[40:41], v[134:135], v[128:129] op_sel_hi:[1,0,1]
.LBB0_910:
	s_waitcnt lgkmcnt(0)
	s_barrier
	ds_read_b128 v[34:37], v1 offset:13568
	ds_read_b128 v[2:5], v94 offset:13056
	ds_read_b128 v[30:33], v94 offset:12800
	ds_read_b128 v[6:9], v94 offset:13072
	ds_read_b128 v[26:29], v94 offset:12816
	ds_read_b128 v[14:17], v94 offset:13088
	ds_read_b128 v[22:25], v94 offset:12832
	ds_read_b128 v[10:13], v94 offset:13104
	ds_read_b128 v[18:21], v94 offset:12848
	ds_read_b32 v73, v95 offset:13312
	s_lshl_b32 s2, s24, 4
	s_add_i32 s16, s18, s2

.LBB0_916:
	s_nop 0
	v_readfirstlane_b32 s100, v92
	v_readfirstlane_b32 s101, v93
	s_sub_u32 s100, s100, m0
	s_subb_u32 s101, s101, 0
	s_waitcnt lgkmcnt(9)
	v_pk_mul_f32 v[114:115], v[34:35], v[74:75] op_sel_hi:[0,1]
	v_pk_mul_f32 v[116:117], v[34:35], v[78:79] op_sel_hi:[0,1]
	s_waitcnt lgkmcnt(7)
	v_pk_fma_f32 v[106:107], v[114:115], v[2:3], 0 op_sel_hi:[1,1,0]
	v_pk_fma_f32 v[108:109], v[114:115], v[30:31], 0 op_sel_hi:[1,1,0]
	v_pk_mul_f32 v[118:119], v[34:35], v[80:81] op_sel_hi:[0,1]
	ds_read_b128 v[66:69], v94 offset:13600
	v_pk_fma_f32 v[106:107], v[116:117], v[4:5], v[106:107]
	v_pk_fma_f32 v[108:109], v[116:117], v[32:33], v[108:109]
	v_pk_mul_f32 v[120:121], v[34:35], v[82:83] op_sel_hi:[0,1]
	ds_read_b128 v[62:65], v94 offset:13616
	s_waitcnt lgkmcnt(7)
	v_pk_fma_f32 v[106:107], v[118:119], v[6:7], v[106:107]
	v_pk_fma_f32 v[108:109], v[118:119], v[26:27], v[108:109]
	v_pk_mul_f32 v[122:123], v[34:35], v[84:85] op_sel_hi:[0,1]
	ds_read_b128 v[58:61], v94 offset:13632
	v_pk_fma_f32 v[106:107], v[120:121], v[8:9], v[106:107]
	v_pk_fma_f32 v[108:109], v[120:121], v[28:29], v[108:109]
	v_pk_mul_f32 v[124:125], v[34:35], v[86:87] op_sel_hi:[0,1]
	ds_read_b128 v[54:57], v94 offset:13648
	s_waitcnt lgkmcnt(7)
	v_pk_fma_f32 v[106:107], v[122:123], v[14:15], v[106:107]
	v_pk_fma_f32 v[108:109], v[122:123], v[22:23], v[108:109]
	v_pk_mul_f32 v[126:127], v[34:35], v[88:89] op_sel_hi:[0,1]
	ds_read_b128 v[50:53], v94 offset:13856
	v_pk_fma_f32 v[106:107], v[124:125], v[16:17], v[106:107]
	v_pk_fma_f32 v[108:109], v[124:125], v[24:25], v[108:109]
	v_pk_mul_f32 v[128:129], v[34:35], v[90:91] op_sel_hi:[0,1]
	ds_read_b128 v[46:49], v94 offset:13872
	s_waitcnt lgkmcnt(7)
	v_pk_fma_f32 v[106:107], v[126:127], v[10:11], v[106:107]
	v_pk_fma_f32 v[108:109], v[126:127], v[18:19], v[108:109]
	ds_read_b128 v[42:45], v94 offset:13888
	v_pk_fma_f32 v[106:107], v[128:129], v[12:13], v[106:107]
	v_pk_fma_f32 v[108:109], v[128:129], v[20:21], v[108:109]
	ds_read_b128 v[38:41], v94 offset:13904
	v_add_f32_e32 v130, v106, v107
	v_add_f32_e32 v131, v108, v109
	ds_read_b32 v0, v95 offset:14112
	v_add_f32_dpp v130, v130, v130 quad_perm:[1,0,3,2] row_mask:0xf bank_mask:0xf bound_ctrl:1
	v_add_f32_dpp v131, v131, v131 quad_perm:[1,0,3,2] row_mask:0xf bank_mask:0xf bound_ctrl:1
	ds_read_b96 v[70:72], v1 offset:14368
	v_add_f32_dpp v130, v130, v130 quad_perm:[2,3,0,1] row_mask:0xf bank_mask:0xf bound_ctrl:1
	v_add_f32_dpp v131, v131, v131 quad_perm:[2,3,0,1] row_mask:0xf bank_mask:0xf bound_ctrl:1
	s_waitcnt lgkmcnt(10)
	v_sub_f32_e32 v130, v73, v130
	v_mul_f32_e32 v130, v35, v130
	v_fma_f32 v131, v36, v130, v131
	v_cvt_pk_bf16_f32 v132, v131, v131
	v_pk_fma_f32 v[74:75], v[2:3], v[130:131], v[114:115] op_sel_hi:[1,0,1]
	v_pk_fma_f32 v[78:79], v[4:5], v[130:131], v[116:117] op_sel_hi:[1,0,1]
	global_store_short v144, v132, s[100:101]
	v_pk_fma_f32 v[80:81], v[6:7], v[130:131], v[118:119] op_sel_hi:[1,0,1]
	v_pk_fma_f32 v[82:83], v[8:9], v[130:131], v[120:121] op_sel_hi:[1,0,1]
	v_pk_fma_f32 v[84:85], v[14:15], v[130:131], v[122:123] op_sel_hi:[1,0,1]
	v_pk_fma_f32 v[86:87], v[16:17], v[130:131], v[124:125] op_sel_hi:[1,0,1]
	v_pk_fma_f32 v[88:89], v[10:11], v[130:131], v[126:127] op_sel_hi:[1,0,1]
	v_pk_fma_f32 v[90:91], v[12:13], v[130:131], v[128:129] op_sel_hi:[1,0,1]
	s_waitcnt lgkmcnt(0)
	v_pk_mul_f32 v[114:115], v[70:71], v[74:75] op_sel_hi:[0,1]
	v_pk_mul_f32 v[116:117], v[70:71], v[78:79] op_sel_hi:[0,1]
	v_pk_fma_f32 v[110:111], v[114:115], v[50:51], 0 op_sel_hi:[1,1,0]
	v_pk_fma_f32 v[112:113], v[114:115], v[66:67], 0 op_sel_hi:[1,1,0]
	v_pk_mul_f32 v[118:119], v[70:71], v[80:81] op_sel_hi:[0,1]
	ds_read_b128 v[30:33], v94 offset:14400
	v_pk_fma_f32 v[110:111], v[116:117], v[52:53], v[110:111]
	v_pk_fma_f32 v[112:113], v[116:117], v[68:69], v[112:113]
	v_pk_mul_f32 v[120:121], v[70:71], v[82:83] op_sel_hi:[0,1]
	ds_read_b128 v[26:29], v94 offset:14416
	v_pk_fma_f32 v[110:111], v[118:119], v[46:47], v[110:111]
	v_pk_fma_f32 v[112:113], v[118:119], v[62:63], v[112:113]
	v_pk_mul_f32 v[122:123], v[70:71], v[84:85] op_sel_hi:[0,1]
	ds_read_b128 v[22:25], v94 offset:14432
	v_pk_fma_f32 v[110:111], v[120:121], v[48:49], v[110:111]
	v_pk_fma_f32 v[112:113], v[120:121], v[64:65], v[112:113]
	v_pk_mul_f32 v[124:125], v[70:71], v[86:87] op_sel_hi:[0,1]
	ds_read_b128 v[18:21], v94 offset:14448
	v_pk_fma_f32 v[110:111], v[122:123], v[42:43], v[110:111]
	v_pk_fma_f32 v[112:113], v[122:123], v[58:59], v[112:113]
	v_pk_mul_f32 v[126:127], v[70:71], v[88:89] op_sel_hi:[0,1]
	ds_read_b128 v[2:5], v94 offset:14656
	v_pk_fma_f32 v[110:111], v[124:125], v[44:45], v[110:111]
	v_pk_fma_f32 v[112:113], v[124:125], v[60:61], v[112:113]
	v_pk_mul_f32 v[128:129], v[70:71], v[90:91] op_sel_hi:[0,1]
	ds_read_b128 v[6:9], v94 offset:14672
	v_pk_fma_f32 v[110:111], v[126:127], v[38:39], v[110:111]
	v_pk_fma_f32 v[112:113], v[126:127], v[54:55], v[112:113]
	ds_read_b128 v[14:17], v94 offset:14688
	v_pk_fma_f32 v[110:111], v[128:129], v[40:41], v[110:111]
	v_pk_fma_f32 v[112:113], v[128:129], v[56:57], v[112:113]
	ds_read_b128 v[10:13], v94 offset:14704
	v_add_f32_e32 v134, v110, v111
	v_add_f32_e32 v135, v112, v113
	ds_read_b32 v73, v95 offset:14912
	v_add_f32_dpp v134, v134, v134 quad_perm:[1,0,3,2] row_mask:0xf bank_mask:0xf bound_ctrl:1
	v_add_f32_dpp v135, v135, v135 quad_perm:[1,0,3,2] row_mask:0xf bank_mask:0xf bound_ctrl:1
	ds_read_b96 v[34:36], v1 offset:15168
	v_add_f32_dpp v134, v134, v134 quad_perm:[2,3,0,1] row_mask:0xf bank_mask:0xf bound_ctrl:1
	v_add_f32_dpp v135, v135, v135 quad_perm:[2,3,0,1] row_mask:0xf bank_mask:0xf bound_ctrl:1
	v_sub_f32_e32 v134, v0, v134
	v_mul_f32_e32 v134, v71, v134
	v_fma_f32 v135, v72, v134, v135
	v_cvt_pk_bf16_f32 v133, v135, v135
	v_pk_fma_f32 v[74:75], v[50:51], v[134:135], v[114:115] op_sel_hi:[1,0,1]
	v_pk_fma_f32 v[78:79], v[52:53], v[134:135], v[116:117] op_sel_hi:[1,0,1]
	global_store_short v145, v133, s[100:101]
	v_pk_fma_f32 v[80:81], v[46:47], v[134:135], v[118:119] op_sel_hi:[1,0,1]
	v_pk_fma_f32 v[82:83], v[48:49], v[134:135], v[120:121] op_sel_hi:[1,0,1]
	v_pk_fma_f32 v[84:85], v[42:43], v[134:135], v[122:123] op_sel_hi:[1,0,1]
	v_pk_fma_f32 v[86:87], v[44:45], v[134:135], v[124:125] op_sel_hi:[1,0,1]
	v_pk_fma_f32 v[88:89], v[38:39], v[134:135], v[126:127] op_sel_hi:[1,0,1]
	v_pk_fma_f32 v[90:91], v[40:41], v[134:135], v[128:129] op_sel_hi:[1,0,1]
	s_waitcnt lgkmcnt(0)
	v_pk_mul_f32 v[114:115], v[34:35], v[74:75] op_sel_hi:[0,1]
	v_pk_mul_f32 v[116:117], v[34:35], v[78:79] op_sel_hi:[0,1]
	v_pk_fma_f32 v[106:107], v[114:115], v[2:3], 0 op_sel_hi:[1,1,0]
	v_pk_fma_f32 v[108:109], v[114:115], v[30:31], 0 op_sel_hi:[1,1,0]
	v_pk_mul_f32 v[118:119], v[34:35], v[80:81] op_sel_hi:[0,1]
	ds_read_b128 v[66:69], v94 offset:15200
	v_pk_fma_f32 v[106:107], v[116:117], v[4:5], v[106:107]
	v_pk_fma_f32 v[108:109], v[116:117], v[32:33], v[108:109]
	v_pk_mul_f32 v[120:121], v[34:35], v[82:83] op_sel_hi:[0,1]
	ds_read_b128 v[62:65], v94 offset:15216
	v_pk_fma_f32 v[106:107], v[118:119], v[6:7], v[106:107]
	v_pk_fma_f32 v[108:109], v[118:119], v[26:27], v[108:109]
	v_pk_mul_f32 v[122:123], v[34:35], v[84:85] op_sel_hi:[0,1]
	ds_read_b128 v[58:61], v94 offset:15232
	v_pk_fma_f32 v[106:107], v[120:121], v[8:9], v[106:107]
	v_pk_fma_f32 v[108:109], v[120:121], v[28:29], v[108:109]
	v_pk_mul_f32 v[124:125], v[34:35], v[86:87] op_sel_hi:[0,1]
	ds_read_b128 v[54:57], v94 offset:15248
	v_pk_fma_f32 v[106:107], v[122:123], v[14:15], v[106:107]
	v_pk_fma_f32 v[108:109], v[122:123], v[22:23], v[108:109]
	v_pk_mul_f32 v[126:127], v[34:35], v[88:89] op_sel_hi:[0,1]
	ds_read_b128 v[50:53], v94 offset:15456
	v_pk_fma_f32 v[106:107], v[124:125], v[16:17], v[106:107]
	v_pk_fma_f32 v[108:109], v[124:125], v[24:25], v[108:109]
	v_pk_mul_f32 v[128:129], v[34:35], v[90:91] op_sel_hi:[0,1]
	ds_read_b128 v[46:49], v94 offset:15472
	v_pk_fma_f32 v[106:107], v[126:127], v[10:11], v[106:107]
	v_pk_fma_f32 v[108:109], v[126:127], v[18:19], v[108:109]
	ds_read_b128 v[42:45], v94 offset:15488
	v_pk_fma_f32 v[106:107], v[128:129], v[12:13], v[106:107]
	v_pk_fma_f32 v[108:109], v[128:129], v[20:21], v[108:109]
	ds_read_b128 v[38:41], v94 offset:15504
	v_add_f32_e32 v130, v106, v107
	v_add_f32_e32 v131, v108, v109
	ds_read_b32 v0, v95 offset:15712
	v_add_f32_dpp v130, v130, v130 quad_perm:[1,0,3,2] row_mask:0xf bank_mask:0xf bound_ctrl:1
	v_add_f32_dpp v131, v131, v131 quad_perm:[1,0,3,2] row_mask:0xf bank_mask:0xf bound_ctrl:1
	ds_read_b96 v[70:72], v1 offset:15968
	v_add_f32_dpp v130, v130, v130 quad_perm:[2,3,0,1] row_mask:0xf bank_mask:0xf bound_ctrl:1
	v_add_f32_dpp v131, v131, v131 quad_perm:[2,3,0,1] row_mask:0xf bank_mask:0xf bound_ctrl:1
	v_sub_f32_e32 v130, v73, v130
	v_mul_f32_e32 v130, v35, v130
	v_fma_f32 v131, v36, v130, v131
	v_cvt_pk_bf16_f32 v132, v131, v131
	v_pk_fma_f32 v[74:75], v[2:3], v[130:131], v[114:115] op_sel_hi:[1,0,1]
	v_pk_fma_f32 v[78:79], v[4:5], v[130:131], v[116:117] op_sel_hi:[1,0,1]
	global_store_short v146, v132, s[100:101]
	v_pk_fma_f32 v[80:81], v[6:7], v[130:131], v[118:119] op_sel_hi:[1,0,1]
	v_pk_fma_f32 v[82:83], v[8:9], v[130:131], v[120:121] op_sel_hi:[1,0,1]
	v_pk_fma_f32 v[84:85], v[14:15], v[130:131], v[122:123] op_sel_hi:[1,0,1]
	v_pk_fma_f32 v[86:87], v[16:17], v[130:131], v[124:125] op_sel_hi:[1,0,1]
	v_pk_fma_f32 v[88:89], v[10:11], v[130:131], v[126:127] op_sel_hi:[1,0,1]
	v_pk_fma_f32 v[90:91], v[12:13], v[130:131], v[128:129] op_sel_hi:[1,0,1]
	s_waitcnt lgkmcnt(0)
	v_pk_mul_f32 v[114:115], v[70:71], v[74:75] op_sel_hi:[0,1]
	v_pk_mul_f32 v[116:117], v[70:71], v[78:79] op_sel_hi:[0,1]
	v_pk_fma_f32 v[110:111], v[114:115], v[50:51], 0 op_sel_hi:[1,1,0]
	v_pk_fma_f32 v[112:113], v[114:115], v[66:67], 0 op_sel_hi:[1,1,0]
	v_pk_mul_f32 v[118:119], v[70:71], v[80:81] op_sel_hi:[0,1]
	ds_read_b128 v[30:33], v94 offset:16000
	v_pk_fma_f32 v[110:111], v[116:117], v[52:53], v[110:111]
	v_pk_fma_f32 v[112:113], v[116:117], v[68:69], v[112:113]
	v_pk_mul_f32 v[120:121], v[70:71], v[82:83] op_sel_hi:[0,1]
	ds_read_b128 v[26:29], v94 offset:16016
	v_pk_fma_f32 v[110:111], v[118:119], v[46:47], v[110:111]
	v_pk_fma_f32 v[112:113], v[118:119], v[62:63], v[112:113]
	v_pk_mul_f32 v[122:123], v[70:71], v[84:85] op_sel_hi:[0,1]
	ds_read_b128 v[22:25], v94 offset:16032
	v_pk_fma_f32 v[110:111], v[120:121], v[48:49], v[110:111]
	v_pk_fma_f32 v[112:113], v[120:121], v[64:65], v[112:113]
	v_pk_mul_f32 v[124:125], v[70:71], v[86:87] op_sel_hi:[0,1]
	ds_read_b128 v[18:21], v94 offset:16048
	v_pk_fma_f32 v[110:111], v[122:123], v[42:43], v[110:111]
	v_pk_fma_f32 v[112:113], v[122:123], v[58:59], v[112:113]
	v_pk_mul_f32 v[126:127], v[70:71], v[88:89] op_sel_hi:[0,1]
	ds_read_b128 v[2:5], v94 offset:16256
	v_pk_fma_f32 v[110:111], v[124:125], v[44:45], v[110:111]
	v_pk_fma_f32 v[112:113], v[124:125], v[60:61], v[112:113]
	v_pk_mul_f32 v[128:129], v[70:71], v[90:91] op_sel_hi:[0,1]
	ds_read_b128 v[6:9], v94 offset:16272
	v_pk_fma_f32 v[110:111], v[126:127], v[38:39], v[110:111]
	v_pk_fma_f32 v[112:113], v[126:127], v[54:55], v[112:113]
	ds_read_b128 v[14:17], v94 offset:16288
	v_pk_fma_f32 v[110:111], v[128:129], v[40:41], v[110:111]
	v_pk_fma_f32 v[112:113], v[128:129], v[56:57], v[112:113]
	ds_read_b128 v[10:13], v94 offset:16304
	v_add_f32_e32 v134, v110, v111
	v_add_f32_e32 v135, v112, v113
	ds_read_b32 v73, v95 offset:16512
	v_add_f32_dpp v134, v134, v134 quad_perm:[1,0,3,2] row_mask:0xf bank_mask:0xf bound_ctrl:1
	v_add_f32_dpp v135, v135, v135 quad_perm:[1,0,3,2] row_mask:0xf bank_mask:0xf bound_ctrl:1
	ds_read_b96 v[34:36], v1 offset:16768
	v_add_f32_dpp v134, v134, v134 quad_perm:[2,3,0,1] row_mask:0xf bank_mask:0xf bound_ctrl:1
	v_add_f32_dpp v135, v135, v135 quad_perm:[2,3,0,1] row_mask:0xf bank_mask:0xf bound_ctrl:1
	v_sub_f32_e32 v134, v0, v134
	v_mul_f32_e32 v134, v71, v134
	v_fma_f32 v135, v72, v134, v135
	v_cvt_pk_bf16_f32 v133, v135, v135
	v_pk_fma_f32 v[74:75], v[50:51], v[134:135], v[114:115] op_sel_hi:[1,0,1]
	v_pk_fma_f32 v[78:79], v[52:53], v[134:135], v[116:117] op_sel_hi:[1,0,1]
	global_store_short v147, v133, s[100:101]
	v_pk_fma_f32 v[80:81], v[46:47], v[134:135], v[118:119] op_sel_hi:[1,0,1]
	v_pk_fma_f32 v[82:83], v[48:49], v[134:135], v[120:121] op_sel_hi:[1,0,1]
	v_pk_fma_f32 v[84:85], v[42:43], v[134:135], v[122:123] op_sel_hi:[1,0,1]
	v_pk_fma_f32 v[86:87], v[44:45], v[134:135], v[124:125] op_sel_hi:[1,0,1]
	v_pk_fma_f32 v[88:89], v[38:39], v[134:135], v[126:127] op_sel_hi:[1,0,1]
	v_pk_fma_f32 v[90:91], v[40:41], v[134:135], v[128:129] op_sel_hi:[1,0,1]
	s_waitcnt lgkmcnt(0)
	v_pk_mul_f32 v[114:115], v[34:35], v[74:75] op_sel_hi:[0,1]
	v_pk_mul_f32 v[116:117], v[34:35], v[78:79] op_sel_hi:[0,1]
	v_pk_fma_f32 v[106:107], v[114:115], v[2:3], 0 op_sel_hi:[1,1,0]
	v_pk_fma_f32 v[108:109], v[114:115], v[30:31], 0 op_sel_hi:[1,1,0]
	v_pk_mul_f32 v[118:119], v[34:35], v[80:81] op_sel_hi:[0,1]
	ds_read_b128 v[66:69], v94 offset:16800
	v_pk_fma_f32 v[106:107], v[116:117], v[4:5], v[106:107]
	v_pk_fma_f32 v[108:109], v[116:117], v[32:33], v[108:109]
	v_pk_mul_f32 v[120:121], v[34:35], v[82:83] op_sel_hi:[0,1]
	ds_read_b128 v[62:65], v94 offset:16816
	v_pk_fma_f32 v[106:107], v[118:119], v[6:7], v[106:107]
	v_pk_fma_f32 v[108:109], v[118:119], v[26:27], v[108:109]
	v_pk_mul_f32 v[122:123], v[34:35], v[84:85] op_sel_hi:[0,1]
	ds_read_b128 v[58:61], v94 offset:16832
	v_pk_fma_f32 v[106:107], v[120:121], v[8:9], v[106:107]
	v_pk_fma_f32 v[108:109], v[120:121], v[28:29], v[108:109]
	v_pk_mul_f32 v[124:125], v[34:35], v[86:87] op_sel_hi:[0,1]
	ds_read_b128 v[54:57], v94 offset:16848
	v_pk_fma_f32 v[106:107], v[122:123], v[14:15], v[106:107]
	v_pk_fma_f32 v[108:109], v[122:123], v[22:23], v[108:109]
	v_pk_mul_f32 v[126:127], v[34:35], v[88:89] op_sel_hi:[0,1]
	ds_read_b128 v[50:53], v94 offset:17056
	v_pk_fma_f32 v[106:107], v[124:125], v[16:17], v[106:107]
	v_pk_fma_f32 v[108:109], v[124:125], v[24:25], v[108:109]
	v_pk_mul_f32 v[128:129], v[34:35], v[90:91] op_sel_hi:[0,1]
	ds_read_b128 v[46:49], v94 offset:17072
	v_pk_fma_f32 v[106:107], v[126:127], v[10:11], v[106:107]
	v_pk_fma_f32 v[108:109], v[126:127], v[18:19], v[108:109]
	ds_read_b128 v[42:45], v94 offset:17088
	v_pk_fma_f32 v[106:107], v[128:129], v[12:13], v[106:107]
	v_pk_fma_f32 v[108:109], v[128:129], v[20:21], v[108:109]
	ds_read_b128 v[38:41], v94 offset:17104
	v_add_f32_e32 v130, v106, v107
	v_add_f32_e32 v131, v108, v109
	ds_read_b32 v0, v95 offset:17312
	v_add_f32_dpp v130, v130, v130 quad_perm:[1,0,3,2] row_mask:0xf bank_mask:0xf bound_ctrl:1
	v_add_f32_dpp v131, v131, v131 quad_perm:[1,0,3,2] row_mask:0xf bank_mask:0xf bound_ctrl:1
	ds_read_b96 v[70:72], v1 offset:17568
	v_add_f32_dpp v130, v130, v130 quad_perm:[2,3,0,1] row_mask:0xf bank_mask:0xf bound_ctrl:1
	v_add_f32_dpp v131, v131, v131 quad_perm:[2,3,0,1] row_mask:0xf bank_mask:0xf bound_ctrl:1
	v_sub_f32_e32 v130, v73, v130
	v_mul_f32_e32 v130, v35, v130
	v_fma_f32 v131, v36, v130, v131
	v_cvt_pk_bf16_f32 v132, v131, v131
	v_pk_fma_f32 v[74:75], v[2:3], v[130:131], v[114:115] op_sel_hi:[1,0,1]
	v_pk_fma_f32 v[78:79], v[4:5], v[130:131], v[116:117] op_sel_hi:[1,0,1]
	global_store_short v148, v132, s[100:101]
	v_pk_fma_f32 v[80:81], v[6:7], v[130:131], v[118:119] op_sel_hi:[1,0,1]
	v_pk_fma_f32 v[82:83], v[8:9], v[130:131], v[120:121] op_sel_hi:[1,0,1]
	v_pk_fma_f32 v[84:85], v[14:15], v[130:131], v[122:123] op_sel_hi:[1,0,1]
	v_pk_fma_f32 v[86:87], v[16:17], v[130:131], v[124:125] op_sel_hi:[1,0,1]
	v_pk_fma_f32 v[88:89], v[10:11], v[130:131], v[126:127] op_sel_hi:[1,0,1]
	v_pk_fma_f32 v[90:91], v[12:13], v[130:131], v[128:129] op_sel_hi:[1,0,1]
	s_waitcnt lgkmcnt(0)
	v_pk_mul_f32 v[114:115], v[70:71], v[74:75] op_sel_hi:[0,1]
	v_pk_mul_f32 v[116:117], v[70:71], v[78:79] op_sel_hi:[0,1]
	v_pk_fma_f32 v[110:111], v[114:115], v[50:51], 0 op_sel_hi:[1,1,0]
	v_pk_fma_f32 v[112:113], v[114:115], v[66:67], 0 op_sel_hi:[1,1,0]
	v_pk_mul_f32 v[118:119], v[70:71], v[80:81] op_sel_hi:[0,1]
	ds_read_b128 v[30:33], v94 offset:17600
	v_pk_fma_f32 v[110:111], v[116:117], v[52:53], v[110:111]
	v_pk_fma_f32 v[112:113], v[116:117], v[68:69], v[112:113]
	v_pk_mul_f32 v[120:121], v[70:71], v[82:83] op_sel_hi:[0,1]
	ds_read_b128 v[26:29], v94 offset:17616
	v_pk_fma_f32 v[110:111], v[118:119], v[46:47], v[110:111]
	v_pk_fma_f32 v[112:113], v[118:119], v[62:63], v[112:113]
	v_pk_mul_f32 v[122:123], v[70:71], v[84:85] op_sel_hi:[0,1]
	ds_read_b128 v[22:25], v94 offset:17632
	v_pk_fma_f32 v[110:111], v[120:121], v[48:49], v[110:111]
	v_pk_fma_f32 v[112:113], v[120:121], v[64:65], v[112:113]
	v_pk_mul_f32 v[124:125], v[70:71], v[86:87] op_sel_hi:[0,1]
	ds_read_b128 v[18:21], v94 offset:17648
	v_pk_fma_f32 v[110:111], v[122:123], v[42:43], v[110:111]
	v_pk_fma_f32 v[112:113], v[122:123], v[58:59], v[112:113]
	v_pk_mul_f32 v[126:127], v[70:71], v[88:89] op_sel_hi:[0,1]
	ds_read_b128 v[2:5], v94 offset:17856
	v_pk_fma_f32 v[110:111], v[124:125], v[44:45], v[110:111]
	v_pk_fma_f32 v[112:113], v[124:125], v[60:61], v[112:113]
	v_pk_mul_f32 v[128:129], v[70:71], v[90:91] op_sel_hi:[0,1]
	ds_read_b128 v[6:9], v94 offset:17872
	v_pk_fma_f32 v[110:111], v[126:127], v[38:39], v[110:111]
	v_pk_fma_f32 v[112:113], v[126:127], v[54:55], v[112:113]
	ds_read_b128 v[14:17], v94 offset:17888
	v_pk_fma_f32 v[110:111], v[128:129], v[40:41], v[110:111]
	v_pk_fma_f32 v[112:113], v[128:129], v[56:57], v[112:113]
	ds_read_b128 v[10:13], v94 offset:17904
	v_add_f32_e32 v134, v110, v111
	v_add_f32_e32 v135, v112, v113
	ds_read_b32 v73, v95 offset:18112
	v_add_f32_dpp v134, v134, v134 quad_perm:[1,0,3,2] row_mask:0xf bank_mask:0xf bound_ctrl:1
	v_add_f32_dpp v135, v135, v135 quad_perm:[1,0,3,2] row_mask:0xf bank_mask:0xf bound_ctrl:1
	ds_read_b96 v[34:36], v1 offset:18368
	v_add_f32_dpp v134, v134, v134 quad_perm:[2,3,0,1] row_mask:0xf bank_mask:0xf bound_ctrl:1
	v_add_f32_dpp v135, v135, v135 quad_perm:[2,3,0,1] row_mask:0xf bank_mask:0xf bound_ctrl:1
	v_sub_f32_e32 v134, v0, v134
	v_mul_f32_e32 v134, v71, v134
	v_fma_f32 v135, v72, v134, v135
	v_cvt_pk_bf16_f32 v133, v135, v135
	v_pk_fma_f32 v[74:75], v[50:51], v[134:135], v[114:115] op_sel_hi:[1,0,1]
	v_pk_fma_f32 v[78:79], v[52:53], v[134:135], v[116:117] op_sel_hi:[1,0,1]
	global_store_short v149, v133, s[100:101]
	v_pk_fma_f32 v[80:81], v[46:47], v[134:135], v[118:119] op_sel_hi:[1,0,1]
	v_pk_fma_f32 v[82:83], v[48:49], v[134:135], v[120:121] op_sel_hi:[1,0,1]
	v_pk_fma_f32 v[84:85], v[42:43], v[134:135], v[122:123] op_sel_hi:[1,0,1]
	v_pk_fma_f32 v[86:87], v[44:45], v[134:135], v[124:125] op_sel_hi:[1,0,1]
	v_pk_fma_f32 v[88:89], v[38:39], v[134:135], v[126:127] op_sel_hi:[1,0,1]
	v_pk_fma_f32 v[90:91], v[40:41], v[134:135], v[128:129] op_sel_hi:[1,0,1]
	s_waitcnt lgkmcnt(0)
	v_pk_mul_f32 v[114:115], v[34:35], v[74:75] op_sel_hi:[0,1]
	v_pk_mul_f32 v[116:117], v[34:35], v[78:79] op_sel_hi:[0,1]
	v_pk_fma_f32 v[106:107], v[114:115], v[2:3], 0 op_sel_hi:[1,1,0]
	v_pk_fma_f32 v[108:109], v[114:115], v[30:31], 0 op_sel_hi:[1,1,0]
	v_pk_mul_f32 v[118:119], v[34:35], v[80:81] op_sel_hi:[0,1]
	ds_read_b128 v[66:69], v94 offset:18400
	v_pk_fma_f32 v[106:107], v[116:117], v[4:5], v[106:107]
	v_pk_fma_f32 v[108:109], v[116:117], v[32:33], v[108:109]
	v_pk_mul_f32 v[120:121], v[34:35], v[82:83] op_sel_hi:[0,1]
	ds_read_b128 v[62:65], v94 offset:18416
	v_pk_fma_f32 v[106:107], v[118:119], v[6:7], v[106:107]
	v_pk_fma_f32 v[108:109], v[118:119], v[26:27], v[108:109]
	v_pk_mul_f32 v[122:123], v[34:35], v[84:85] op_sel_hi:[0,1]
	ds_read_b128 v[58:61], v94 offset:18432
	v_pk_fma_f32 v[106:107], v[120:121], v[8:9], v[106:107]
	v_pk_fma_f32 v[108:109], v[120:121], v[28:29], v[108:109]
	v_pk_mul_f32 v[124:125], v[34:35], v[86:87] op_sel_hi:[0,1]
	ds_read_b128 v[54:57], v94 offset:18448
	v_pk_fma_f32 v[106:107], v[122:123], v[14:15], v[106:107]
	v_pk_fma_f32 v[108:109], v[122:123], v[22:23], v[108:109]
	v_pk_mul_f32 v[126:127], v[34:35], v[88:89] op_sel_hi:[0,1]
	ds_read_b128 v[50:53], v94 offset:18656
	v_pk_fma_f32 v[106:107], v[124:125], v[16:17], v[106:107]
	v_pk_fma_f32 v[108:109], v[124:125], v[24:25], v[108:109]
	v_pk_mul_f32 v[128:129], v[34:35], v[90:91] op_sel_hi:[0,1]
	ds_read_b128 v[46:49], v94 offset:18672
	v_pk_fma_f32 v[106:107], v[126:127], v[10:11], v[106:107]
	v_pk_fma_f32 v[108:109], v[126:127], v[18:19], v[108:109]
	ds_read_b128 v[42:45], v94 offset:18688
	v_pk_fma_f32 v[106:107], v[128:129], v[12:13], v[106:107]
	v_pk_fma_f32 v[108:109], v[128:129], v[20:21], v[108:109]
	ds_read_b128 v[38:41], v94 offset:18704
	v_add_f32_e32 v130, v106, v107
	v_add_f32_e32 v131, v108, v109
	ds_read_b32 v0, v95 offset:18912
	v_add_f32_dpp v130, v130, v130 quad_perm:[1,0,3,2] row_mask:0xf bank_mask:0xf bound_ctrl:1
	v_add_f32_dpp v131, v131, v131 quad_perm:[1,0,3,2] row_mask:0xf bank_mask:0xf bound_ctrl:1
	ds_read_b96 v[70:72], v1 offset:19168
	v_add_f32_dpp v130, v130, v130 quad_perm:[2,3,0,1] row_mask:0xf bank_mask:0xf bound_ctrl:1
	v_add_f32_dpp v131, v131, v131 quad_perm:[2,3,0,1] row_mask:0xf bank_mask:0xf bound_ctrl:1
	v_sub_f32_e32 v130, v73, v130
	v_mul_f32_e32 v130, v35, v130
	v_fma_f32 v131, v36, v130, v131
	v_cvt_pk_bf16_f32 v132, v131, v131
	v_pk_fma_f32 v[74:75], v[2:3], v[130:131], v[114:115] op_sel_hi:[1,0,1]
	v_pk_fma_f32 v[78:79], v[4:5], v[130:131], v[116:117] op_sel_hi:[1,0,1]
	global_store_short v150, v132, s[100:101]
	v_pk_fma_f32 v[80:81], v[6:7], v[130:131], v[118:119] op_sel_hi:[1,0,1]
	v_pk_fma_f32 v[82:83], v[8:9], v[130:131], v[120:121] op_sel_hi:[1,0,1]
	v_pk_fma_f32 v[84:85], v[14:15], v[130:131], v[122:123] op_sel_hi:[1,0,1]
	v_pk_fma_f32 v[86:87], v[16:17], v[130:131], v[124:125] op_sel_hi:[1,0,1]
	v_pk_fma_f32 v[88:89], v[10:11], v[130:131], v[126:127] op_sel_hi:[1,0,1]
	v_pk_fma_f32 v[90:91], v[12:13], v[130:131], v[128:129] op_sel_hi:[1,0,1]
	s_waitcnt lgkmcnt(0)
	v_pk_mul_f32 v[114:115], v[70:71], v[74:75] op_sel_hi:[0,1]
	v_pk_mul_f32 v[116:117], v[70:71], v[78:79] op_sel_hi:[0,1]
	v_pk_fma_f32 v[110:111], v[114:115], v[50:51], 0 op_sel_hi:[1,1,0]
	v_pk_fma_f32 v[112:113], v[114:115], v[66:67], 0 op_sel_hi:[1,1,0]
	v_pk_mul_f32 v[118:119], v[70:71], v[80:81] op_sel_hi:[0,1]
	ds_read_b128 v[30:33], v94 offset:19200
	v_pk_fma_f32 v[110:111], v[116:117], v[52:53], v[110:111]
	v_pk_fma_f32 v[112:113], v[116:117], v[68:69], v[112:113]
	v_pk_mul_f32 v[120:121], v[70:71], v[82:83] op_sel_hi:[0,1]
	ds_read_b128 v[26:29], v94 offset:19216
	v_pk_fma_f32 v[110:111], v[118:119], v[46:47], v[110:111]
	v_pk_fma_f32 v[112:113], v[118:119], v[62:63], v[112:113]
	v_pk_mul_f32 v[122:123], v[70:71], v[84:85] op_sel_hi:[0,1]
	ds_read_b128 v[22:25], v94 offset:19232
	v_pk_fma_f32 v[110:111], v[120:121], v[48:49], v[110:111]
	v_pk_fma_f32 v[112:113], v[120:121], v[64:65], v[112:113]
	v_pk_mul_f32 v[124:125], v[70:71], v[86:87] op_sel_hi:[0,1]
	ds_read_b128 v[18:21], v94 offset:19248
	v_pk_fma_f32 v[110:111], v[122:123], v[42:43], v[110:111]
	v_pk_fma_f32 v[112:113], v[122:123], v[58:59], v[112:113]
	v_pk_mul_f32 v[126:127], v[70:71], v[88:89] op_sel_hi:[0,1]
	ds_read_b128 v[2:5], v94 offset:19456
	v_pk_fma_f32 v[110:111], v[124:125], v[44:45], v[110:111]
	v_pk_fma_f32 v[112:113], v[124:125], v[60:61], v[112:113]
	v_pk_mul_f32 v[128:129], v[70:71], v[90:91] op_sel_hi:[0,1]
	ds_read_b128 v[6:9], v94 offset:19472
	v_pk_fma_f32 v[110:111], v[126:127], v[38:39], v[110:111]
	v_pk_fma_f32 v[112:113], v[126:127], v[54:55], v[112:113]
	ds_read_b128 v[14:17], v94 offset:19488
	v_pk_fma_f32 v[110:111], v[128:129], v[40:41], v[110:111]
	v_pk_fma_f32 v[112:113], v[128:129], v[56:57], v[112:113]
	ds_read_b128 v[10:13], v94 offset:19504
	v_add_f32_e32 v134, v110, v111
	v_add_f32_e32 v135, v112, v113
	ds_read_b32 v73, v95 offset:19712
	v_add_f32_dpp v134, v134, v134 quad_perm:[1,0,3,2] row_mask:0xf bank_mask:0xf bound_ctrl:1
	v_add_f32_dpp v135, v135, v135 quad_perm:[1,0,3,2] row_mask:0xf bank_mask:0xf bound_ctrl:1
	ds_read_b96 v[34:36], v1 offset:19968
	v_add_f32_dpp v134, v134, v134 quad_perm:[2,3,0,1] row_mask:0xf bank_mask:0xf bound_ctrl:1
	v_add_f32_dpp v135, v135, v135 quad_perm:[2,3,0,1] row_mask:0xf bank_mask:0xf bound_ctrl:1
	v_sub_f32_e32 v134, v0, v134
	v_mul_f32_e32 v134, v71, v134
	v_fma_f32 v135, v72, v134, v135
	v_cvt_pk_bf16_f32 v133, v135, v135
	v_pk_fma_f32 v[74:75], v[50:51], v[134:135], v[114:115] op_sel_hi:[1,0,1]
	v_pk_fma_f32 v[78:79], v[52:53], v[134:135], v[116:117] op_sel_hi:[1,0,1]
	global_store_short v151, v133, s[100:101]
	v_pk_fma_f32 v[80:81], v[46:47], v[134:135], v[118:119] op_sel_hi:[1,0,1]
	v_pk_fma_f32 v[82:83], v[48:49], v[134:135], v[120:121] op_sel_hi:[1,0,1]
	v_pk_fma_f32 v[84:85], v[42:43], v[134:135], v[122:123] op_sel_hi:[1,0,1]
	v_pk_fma_f32 v[86:87], v[44:45], v[134:135], v[124:125] op_sel_hi:[1,0,1]
	v_pk_fma_f32 v[88:89], v[38:39], v[134:135], v[126:127] op_sel_hi:[1,0,1]
	v_pk_fma_f32 v[90:91], v[40:41], v[134:135], v[128:129] op_sel_hi:[1,0,1]
	s_waitcnt lgkmcnt(0)
	v_pk_mul_f32 v[114:115], v[34:35], v[74:75] op_sel_hi:[0,1]
	v_pk_mul_f32 v[116:117], v[34:35], v[78:79] op_sel_hi:[0,1]
	v_pk_fma_f32 v[106:107], v[114:115], v[2:3], 0 op_sel_hi:[1,1,0]
	v_pk_fma_f32 v[108:109], v[114:115], v[30:31], 0 op_sel_hi:[1,1,0]
	v_pk_mul_f32 v[118:119], v[34:35], v[80:81] op_sel_hi:[0,1]
	ds_read_b128 v[66:69], v94 offset:20000
	v_pk_fma_f32 v[106:107], v[116:117], v[4:5], v[106:107]
	v_pk_fma_f32 v[108:109], v[116:117], v[32:33], v[108:109]
	v_pk_mul_f32 v[120:121], v[34:35], v[82:83] op_sel_hi:[0,1]
	ds_read_b128 v[62:65], v94 offset:20016
	v_pk_fma_f32 v[106:107], v[118:119], v[6:7], v[106:107]
	v_pk_fma_f32 v[108:109], v[118:119], v[26:27], v[108:109]
	v_pk_mul_f32 v[122:123], v[34:35], v[84:85] op_sel_hi:[0,1]
	ds_read_b128 v[58:61], v94 offset:20032
	v_pk_fma_f32 v[106:107], v[120:121], v[8:9], v[106:107]
	v_pk_fma_f32 v[108:109], v[120:121], v[28:29], v[108:109]
	v_pk_mul_f32 v[124:125], v[34:35], v[86:87] op_sel_hi:[0,1]
	ds_read_b128 v[54:57], v94 offset:20048
	v_pk_fma_f32 v[106:107], v[122:123], v[14:15], v[106:107]
	v_pk_fma_f32 v[108:109], v[122:123], v[22:23], v[108:109]
	v_pk_mul_f32 v[126:127], v[34:35], v[88:89] op_sel_hi:[0,1]
	ds_read_b128 v[50:53], v94 offset:20256
	v_pk_fma_f32 v[106:107], v[124:125], v[16:17], v[106:107]
	v_pk_fma_f32 v[108:109], v[124:125], v[24:25], v[108:109]
	v_pk_mul_f32 v[128:129], v[34:35], v[90:91] op_sel_hi:[0,1]
	ds_read_b128 v[46:49], v94 offset:20272
	v_pk_fma_f32 v[106:107], v[126:127], v[10:11], v[106:107]
	v_pk_fma_f32 v[108:109], v[126:127], v[18:19], v[108:109]
	ds_read_b128 v[42:45], v94 offset:20288
	v_pk_fma_f32 v[106:107], v[128:129], v[12:13], v[106:107]
	v_pk_fma_f32 v[108:109], v[128:129], v[20:21], v[108:109]
	ds_read_b128 v[38:41], v94 offset:20304
	v_add_f32_e32 v130, v106, v107
	v_add_f32_e32 v131, v108, v109
	ds_read_b32 v0, v95 offset:20512
	v_add_f32_dpp v130, v130, v130 quad_perm:[1,0,3,2] row_mask:0xf bank_mask:0xf bound_ctrl:1
	v_add_f32_dpp v131, v131, v131 quad_perm:[1,0,3,2] row_mask:0xf bank_mask:0xf bound_ctrl:1
	ds_read_b96 v[70:72], v1 offset:20768
	v_add_f32_dpp v130, v130, v130 quad_perm:[2,3,0,1] row_mask:0xf bank_mask:0xf bound_ctrl:1
	v_add_f32_dpp v131, v131, v131 quad_perm:[2,3,0,1] row_mask:0xf bank_mask:0xf bound_ctrl:1
	v_sub_f32_e32 v130, v73, v130
	v_mul_f32_e32 v130, v35, v130
	v_fma_f32 v131, v36, v130, v131
	v_cvt_pk_bf16_f32 v132, v131, v131
	v_pk_fma_f32 v[74:75], v[2:3], v[130:131], v[114:115] op_sel_hi:[1,0,1]
	v_pk_fma_f32 v[78:79], v[4:5], v[130:131], v[116:117] op_sel_hi:[1,0,1]
	global_store_short v152, v132, s[100:101]
	v_pk_fma_f32 v[80:81], v[6:7], v[130:131], v[118:119] op_sel_hi:[1,0,1]
	v_pk_fma_f32 v[82:83], v[8:9], v[130:131], v[120:121] op_sel_hi:[1,0,1]
	v_pk_fma_f32 v[84:85], v[14:15], v[130:131], v[122:123] op_sel_hi:[1,0,1]
	v_pk_fma_f32 v[86:87], v[16:17], v[130:131], v[124:125] op_sel_hi:[1,0,1]
	v_pk_fma_f32 v[88:89], v[10:11], v[130:131], v[126:127] op_sel_hi:[1,0,1]
	v_pk_fma_f32 v[90:91], v[12:13], v[130:131], v[128:129] op_sel_hi:[1,0,1]
	s_waitcnt lgkmcnt(0)
	v_pk_mul_f32 v[114:115], v[70:71], v[74:75] op_sel_hi:[0,1]
	v_pk_mul_f32 v[116:117], v[70:71], v[78:79] op_sel_hi:[0,1]
	v_pk_fma_f32 v[110:111], v[114:115], v[50:51], 0 op_sel_hi:[1,1,0]
	v_pk_fma_f32 v[112:113], v[114:115], v[66:67], 0 op_sel_hi:[1,1,0]
	v_pk_mul_f32 v[118:119], v[70:71], v[80:81] op_sel_hi:[0,1]
	ds_read_b128 v[30:33], v94 offset:20800
	v_pk_fma_f32 v[110:111], v[116:117], v[52:53], v[110:111]
	v_pk_fma_f32 v[112:113], v[116:117], v[68:69], v[112:113]
	v_pk_mul_f32 v[120:121], v[70:71], v[82:83] op_sel_hi:[0,1]
	ds_read_b128 v[26:29], v94 offset:20816
	v_pk_fma_f32 v[110:111], v[118:119], v[46:47], v[110:111]
	v_pk_fma_f32 v[112:113], v[118:119], v[62:63], v[112:113]
	v_pk_mul_f32 v[122:123], v[70:71], v[84:85] op_sel_hi:[0,1]
	ds_read_b128 v[22:25], v94 offset:20832
	v_pk_fma_f32 v[110:111], v[120:121], v[48:49], v[110:111]
	v_pk_fma_f32 v[112:113], v[120:121], v[64:65], v[112:113]
	v_pk_mul_f32 v[124:125], v[70:71], v[86:87] op_sel_hi:[0,1]
	ds_read_b128 v[18:21], v94 offset:20848
	v_pk_fma_f32 v[110:111], v[122:123], v[42:43], v[110:111]
	v_pk_fma_f32 v[112:113], v[122:123], v[58:59], v[112:113]
	v_pk_mul_f32 v[126:127], v[70:71], v[88:89] op_sel_hi:[0,1]
	ds_read_b128 v[2:5], v94 offset:21056
	v_pk_fma_f32 v[110:111], v[124:125], v[44:45], v[110:111]
	v_pk_fma_f32 v[112:113], v[124:125], v[60:61], v[112:113]
	v_pk_mul_f32 v[128:129], v[70:71], v[90:91] op_sel_hi:[0,1]
	ds_read_b128 v[6:9], v94 offset:21072
	v_pk_fma_f32 v[110:111], v[126:127], v[38:39], v[110:111]
	v_pk_fma_f32 v[112:113], v[126:127], v[54:55], v[112:113]
	ds_read_b128 v[14:17], v94 offset:21088
	v_pk_fma_f32 v[110:111], v[128:129], v[40:41], v[110:111]
	v_pk_fma_f32 v[112:113], v[128:129], v[56:57], v[112:113]
	ds_read_b128 v[10:13], v94 offset:21104
	v_add_f32_e32 v134, v110, v111
	v_add_f32_e32 v135, v112, v113
	ds_read_b32 v73, v95 offset:21312
	v_add_f32_dpp v134, v134, v134 quad_perm:[1,0,3,2] row_mask:0xf bank_mask:0xf bound_ctrl:1
	v_add_f32_dpp v135, v135, v135 quad_perm:[1,0,3,2] row_mask:0xf bank_mask:0xf bound_ctrl:1
	ds_read_b96 v[34:36], v1 offset:21568
	v_add_f32_dpp v134, v134, v134 quad_perm:[2,3,0,1] row_mask:0xf bank_mask:0xf bound_ctrl:1
	v_add_f32_dpp v135, v135, v135 quad_perm:[2,3,0,1] row_mask:0xf bank_mask:0xf bound_ctrl:1
	v_sub_f32_e32 v134, v0, v134
	v_mul_f32_e32 v134, v71, v134
	v_fma_f32 v135, v72, v134, v135
	v_cvt_pk_bf16_f32 v133, v135, v135
	v_pk_fma_f32 v[74:75], v[50:51], v[134:135], v[114:115] op_sel_hi:[1,0,1]
	v_pk_fma_f32 v[78:79], v[52:53], v[134:135], v[116:117] op_sel_hi:[1,0,1]
	global_store_short v153, v133, s[100:101]
	v_pk_fma_f32 v[80:81], v[46:47], v[134:135], v[118:119] op_sel_hi:[1,0,1]
	v_pk_fma_f32 v[82:83], v[48:49], v[134:135], v[120:121] op_sel_hi:[1,0,1]
	v_pk_fma_f32 v[84:85], v[42:43], v[134:135], v[122:123] op_sel_hi:[1,0,1]
	v_pk_fma_f32 v[86:87], v[44:45], v[134:135], v[124:125] op_sel_hi:[1,0,1]
	v_pk_fma_f32 v[88:89], v[38:39], v[134:135], v[126:127] op_sel_hi:[1,0,1]
	v_pk_fma_f32 v[90:91], v[40:41], v[134:135], v[128:129] op_sel_hi:[1,0,1]
	s_waitcnt lgkmcnt(0)
	v_pk_mul_f32 v[114:115], v[34:35], v[74:75] op_sel_hi:[0,1]
	v_pk_mul_f32 v[116:117], v[34:35], v[78:79] op_sel_hi:[0,1]
	v_pk_fma_f32 v[106:107], v[114:115], v[2:3], 0 op_sel_hi:[1,1,0]
	v_pk_fma_f32 v[108:109], v[114:115], v[30:31], 0 op_sel_hi:[1,1,0]
	v_pk_mul_f32 v[118:119], v[34:35], v[80:81] op_sel_hi:[0,1]
	ds_read_b128 v[66:69], v94 offset:21600
	v_pk_fma_f32 v[106:107], v[116:117], v[4:5], v[106:107]
	v_pk_fma_f32 v[108:109], v[116:117], v[32:33], v[108:109]
	v_pk_mul_f32 v[120:121], v[34:35], v[82:83] op_sel_hi:[0,1]
	ds_read_b128 v[62:65], v94 offset:21616
	v_pk_fma_f32 v[106:107], v[118:119], v[6:7], v[106:107]
	v_pk_fma_f32 v[108:109], v[118:119], v[26:27], v[108:109]
	v_pk_mul_f32 v[122:123], v[34:35], v[84:85] op_sel_hi:[0,1]
	ds_read_b128 v[58:61], v94 offset:21632
	v_pk_fma_f32 v[106:107], v[120:121], v[8:9], v[106:107]
	v_pk_fma_f32 v[108:109], v[120:121], v[28:29], v[108:109]
	v_pk_mul_f32 v[124:125], v[34:35], v[86:87] op_sel_hi:[0,1]
	ds_read_b128 v[54:57], v94 offset:21648
	v_pk_fma_f32 v[106:107], v[122:123], v[14:15], v[106:107]
	v_pk_fma_f32 v[108:109], v[122:123], v[22:23], v[108:109]
	v_pk_mul_f32 v[126:127], v[34:35], v[88:89] op_sel_hi:[0,1]
	ds_read_b128 v[50:53], v94 offset:21856
	v_pk_fma_f32 v[106:107], v[124:125], v[16:17], v[106:107]
	v_pk_fma_f32 v[108:109], v[124:125], v[24:25], v[108:109]
	v_pk_mul_f32 v[128:129], v[34:35], v[90:91] op_sel_hi:[0,1]
	ds_read_b128 v[46:49], v94 offset:21872
	v_pk_fma_f32 v[106:107], v[126:127], v[10:11], v[106:107]
	v_pk_fma_f32 v[108:109], v[126:127], v[18:19], v[108:109]
	ds_read_b128 v[42:45], v94 offset:21888
	v_pk_fma_f32 v[106:107], v[128:129], v[12:13], v[106:107]
	v_pk_fma_f32 v[108:109], v[128:129], v[20:21], v[108:109]
	ds_read_b128 v[38:41], v94 offset:21904
	v_add_f32_e32 v130, v106, v107
	v_add_f32_e32 v131, v108, v109
	ds_read_b32 v0, v95 offset:22112
	v_add_f32_dpp v130, v130, v130 quad_perm:[1,0,3,2] row_mask:0xf bank_mask:0xf bound_ctrl:1
	v_add_f32_dpp v131, v131, v131 quad_perm:[1,0,3,2] row_mask:0xf bank_mask:0xf bound_ctrl:1
	ds_read_b96 v[70:72], v1 offset:22368
	v_add_f32_dpp v130, v130, v130 quad_perm:[2,3,0,1] row_mask:0xf bank_mask:0xf bound_ctrl:1
	v_add_f32_dpp v131, v131, v131 quad_perm:[2,3,0,1] row_mask:0xf bank_mask:0xf bound_ctrl:1
	v_sub_f32_e32 v130, v73, v130
	v_mul_f32_e32 v130, v35, v130
	v_fma_f32 v131, v36, v130, v131
	v_cvt_pk_bf16_f32 v132, v131, v131
	v_pk_fma_f32 v[74:75], v[2:3], v[130:131], v[114:115] op_sel_hi:[1,0,1]
	v_pk_fma_f32 v[78:79], v[4:5], v[130:131], v[116:117] op_sel_hi:[1,0,1]
	global_store_short v154, v132, s[100:101]
	v_pk_fma_f32 v[80:81], v[6:7], v[130:131], v[118:119] op_sel_hi:[1,0,1]
	v_pk_fma_f32 v[82:83], v[8:9], v[130:131], v[120:121] op_sel_hi:[1,0,1]
	v_pk_fma_f32 v[84:85], v[14:15], v[130:131], v[122:123] op_sel_hi:[1,0,1]
	v_pk_fma_f32 v[86:87], v[16:17], v[130:131], v[124:125] op_sel_hi:[1,0,1]
	v_pk_fma_f32 v[88:89], v[10:11], v[130:131], v[126:127] op_sel_hi:[1,0,1]
	v_pk_fma_f32 v[90:91], v[12:13], v[130:131], v[128:129] op_sel_hi:[1,0,1]
	s_waitcnt lgkmcnt(0)
	v_pk_mul_f32 v[114:115], v[70:71], v[74:75] op_sel_hi:[0,1]
	v_pk_mul_f32 v[116:117], v[70:71], v[78:79] op_sel_hi:[0,1]
	v_pk_fma_f32 v[110:111], v[114:115], v[50:51], 0 op_sel_hi:[1,1,0]
	v_pk_fma_f32 v[112:113], v[114:115], v[66:67], 0 op_sel_hi:[1,1,0]
	v_pk_mul_f32 v[118:119], v[70:71], v[80:81] op_sel_hi:[0,1]
	ds_read_b128 v[30:33], v94 offset:22400
	v_pk_fma_f32 v[110:111], v[116:117], v[52:53], v[110:111]
	v_pk_fma_f32 v[112:113], v[116:117], v[68:69], v[112:113]
	v_pk_mul_f32 v[120:121], v[70:71], v[82:83] op_sel_hi:[0,1]
	ds_read_b128 v[26:29], v94 offset:22416
	v_pk_fma_f32 v[110:111], v[118:119], v[46:47], v[110:111]
	v_pk_fma_f32 v[112:113], v[118:119], v[62:63], v[112:113]
	v_pk_mul_f32 v[122:123], v[70:71], v[84:85] op_sel_hi:[0,1]
	ds_read_b128 v[22:25], v94 offset:22432
	v_pk_fma_f32 v[110:111], v[120:121], v[48:49], v[110:111]
	v_pk_fma_f32 v[112:113], v[120:121], v[64:65], v[112:113]
	v_pk_mul_f32 v[124:125], v[70:71], v[86:87] op_sel_hi:[0,1]
	ds_read_b128 v[18:21], v94 offset:22448
	v_pk_fma_f32 v[110:111], v[122:123], v[42:43], v[110:111]
	v_pk_fma_f32 v[112:113], v[122:123], v[58:59], v[112:113]
	v_pk_mul_f32 v[126:127], v[70:71], v[88:89] op_sel_hi:[0,1]
	ds_read_b128 v[2:5], v94 offset:22656
	v_pk_fma_f32 v[110:111], v[124:125], v[44:45], v[110:111]
	v_pk_fma_f32 v[112:113], v[124:125], v[60:61], v[112:113]
	v_pk_mul_f32 v[128:129], v[70:71], v[90:91] op_sel_hi:[0,1]
	ds_read_b128 v[6:9], v94 offset:22672
	v_pk_fma_f32 v[110:111], v[126:127], v[38:39], v[110:111]
	v_pk_fma_f32 v[112:113], v[126:127], v[54:55], v[112:113]
	ds_read_b128 v[14:17], v94 offset:22688
	v_pk_fma_f32 v[110:111], v[128:129], v[40:41], v[110:111]
	v_pk_fma_f32 v[112:113], v[128:129], v[56:57], v[112:113]
	ds_read_b128 v[10:13], v94 offset:22704
	v_add_f32_e32 v134, v110, v111
	v_add_f32_e32 v135, v112, v113
	ds_read_b32 v73, v95 offset:22912
	v_add_f32_dpp v134, v134, v134 quad_perm:[1,0,3,2] row_mask:0xf bank_mask:0xf bound_ctrl:1
	v_add_f32_dpp v135, v135, v135 quad_perm:[1,0,3,2] row_mask:0xf bank_mask:0xf bound_ctrl:1
	ds_read_b96 v[34:36], v1 offset:23168
	v_add_f32_dpp v134, v134, v134 quad_perm:[2,3,0,1] row_mask:0xf bank_mask:0xf bound_ctrl:1
	v_add_f32_dpp v135, v135, v135 quad_perm:[2,3,0,1] row_mask:0xf bank_mask:0xf bound_ctrl:1
	v_sub_f32_e32 v134, v0, v134
	v_mul_f32_e32 v134, v71, v134
	v_fma_f32 v135, v72, v134, v135
	v_cvt_pk_bf16_f32 v133, v135, v135
	v_pk_fma_f32 v[74:75], v[50:51], v[134:135], v[114:115] op_sel_hi:[1,0,1]
	v_pk_fma_f32 v[78:79], v[52:53], v[134:135], v[116:117] op_sel_hi:[1,0,1]
	global_store_short v155, v133, s[100:101]
	v_pk_fma_f32 v[80:81], v[46:47], v[134:135], v[118:119] op_sel_hi:[1,0,1]
	v_pk_fma_f32 v[82:83], v[48:49], v[134:135], v[120:121] op_sel_hi:[1,0,1]
	v_pk_fma_f32 v[84:85], v[42:43], v[134:135], v[122:123] op_sel_hi:[1,0,1]
	v_pk_fma_f32 v[86:87], v[44:45], v[134:135], v[124:125] op_sel_hi:[1,0,1]
	v_pk_fma_f32 v[88:89], v[38:39], v[134:135], v[126:127] op_sel_hi:[1,0,1]
	v_pk_fma_f32 v[90:91], v[40:41], v[134:135], v[128:129] op_sel_hi:[1,0,1]
	s_waitcnt lgkmcnt(0)
	v_pk_mul_f32 v[114:115], v[34:35], v[74:75] op_sel_hi:[0,1]
	v_pk_mul_f32 v[116:117], v[34:35], v[78:79] op_sel_hi:[0,1]
	v_pk_fma_f32 v[106:107], v[114:115], v[2:3], 0 op_sel_hi:[1,1,0]
	v_pk_fma_f32 v[108:109], v[114:115], v[30:31], 0 op_sel_hi:[1,1,0]
	v_pk_mul_f32 v[118:119], v[34:35], v[80:81] op_sel_hi:[0,1]
	ds_read_b128 v[66:69], v94 offset:23200
	v_pk_fma_f32 v[106:107], v[116:117], v[4:5], v[106:107]
	v_pk_fma_f32 v[108:109], v[116:117], v[32:33], v[108:109]
	v_pk_mul_f32 v[120:121], v[34:35], v[82:83] op_sel_hi:[0,1]
	ds_read_b128 v[62:65], v94 offset:23216
	v_pk_fma_f32 v[106:107], v[118:119], v[6:7], v[106:107]
	v_pk_fma_f32 v[108:109], v[118:119], v[26:27], v[108:109]
	v_pk_mul_f32 v[122:123], v[34:35], v[84:85] op_sel_hi:[0,1]
	ds_read_b128 v[58:61], v94 offset:23232
	v_pk_fma_f32 v[106:107], v[120:121], v[8:9], v[106:107]
	v_pk_fma_f32 v[108:109], v[120:121], v[28:29], v[108:109]
	v_pk_mul_f32 v[124:125], v[34:35], v[86:87] op_sel_hi:[0,1]
	ds_read_b128 v[54:57], v94 offset:23248
	v_pk_fma_f32 v[106:107], v[122:123], v[14:15], v[106:107]
	v_pk_fma_f32 v[108:109], v[122:123], v[22:23], v[108:109]
	v_pk_mul_f32 v[126:127], v[34:35], v[88:89] op_sel_hi:[0,1]
	ds_read_b128 v[50:53], v94 offset:23456
	v_pk_fma_f32 v[106:107], v[124:125], v[16:17], v[106:107]
	v_pk_fma_f32 v[108:109], v[124:125], v[24:25], v[108:109]
	v_pk_mul_f32 v[128:129], v[34:35], v[90:91] op_sel_hi:[0,1]
	ds_read_b128 v[46:49], v94 offset:23472
	v_pk_fma_f32 v[106:107], v[126:127], v[10:11], v[106:107]
	v_pk_fma_f32 v[108:109], v[126:127], v[18:19], v[108:109]
	ds_read_b128 v[42:45], v94 offset:23488
	v_pk_fma_f32 v[106:107], v[128:129], v[12:13], v[106:107]
	v_pk_fma_f32 v[108:109], v[128:129], v[20:21], v[108:109]
	ds_read_b128 v[38:41], v94 offset:23504
	v_add_f32_e32 v130, v106, v107
	v_add_f32_e32 v131, v108, v109
	ds_read_b32 v0, v95 offset:23712
	v_add_f32_dpp v130, v130, v130 quad_perm:[1,0,3,2] row_mask:0xf bank_mask:0xf bound_ctrl:1
	v_add_f32_dpp v131, v131, v131 quad_perm:[1,0,3,2] row_mask:0xf bank_mask:0xf bound_ctrl:1
	ds_read_b96 v[70:72], v1 offset:23968
	v_add_f32_dpp v130, v130, v130 quad_perm:[2,3,0,1] row_mask:0xf bank_mask:0xf bound_ctrl:1
	v_add_f32_dpp v131, v131, v131 quad_perm:[2,3,0,1] row_mask:0xf bank_mask:0xf bound_ctrl:1
	v_sub_f32_e32 v130, v73, v130
	v_mul_f32_e32 v130, v35, v130
	v_fma_f32 v131, v36, v130, v131
	v_cvt_pk_bf16_f32 v132, v131, v131
	v_pk_fma_f32 v[74:75], v[2:3], v[130:131], v[114:115] op_sel_hi:[1,0,1]
	v_pk_fma_f32 v[78:79], v[4:5], v[130:131], v[116:117] op_sel_hi:[1,0,1]
	global_store_short v156, v132, s[100:101]
	v_pk_fma_f32 v[80:81], v[6:7], v[130:131], v[118:119] op_sel_hi:[1,0,1]
	v_pk_fma_f32 v[82:83], v[8:9], v[130:131], v[120:121] op_sel_hi:[1,0,1]
	v_pk_fma_f32 v[84:85], v[14:15], v[130:131], v[122:123] op_sel_hi:[1,0,1]
	v_pk_fma_f32 v[86:87], v[16:17], v[130:131], v[124:125] op_sel_hi:[1,0,1]
	v_pk_fma_f32 v[88:89], v[10:11], v[130:131], v[126:127] op_sel_hi:[1,0,1]
	v_pk_fma_f32 v[90:91], v[12:13], v[130:131], v[128:129] op_sel_hi:[1,0,1]
	s_waitcnt lgkmcnt(0)
	v_pk_mul_f32 v[114:115], v[70:71], v[74:75] op_sel_hi:[0,1]
	v_pk_mul_f32 v[116:117], v[70:71], v[78:79] op_sel_hi:[0,1]
	v_pk_fma_f32 v[110:111], v[114:115], v[50:51], 0 op_sel_hi:[1,1,0]
	v_pk_fma_f32 v[112:113], v[114:115], v[66:67], 0 op_sel_hi:[1,1,0]
	v_pk_mul_f32 v[118:119], v[70:71], v[80:81] op_sel_hi:[0,1]
	ds_read_b128 v[30:33], v94 offset:24000
	v_pk_fma_f32 v[110:111], v[116:117], v[52:53], v[110:111]
	v_pk_fma_f32 v[112:113], v[116:117], v[68:69], v[112:113]
	v_pk_mul_f32 v[120:121], v[70:71], v[82:83] op_sel_hi:[0,1]
	ds_read_b128 v[26:29], v94 offset:24016
	v_pk_fma_f32 v[110:111], v[118:119], v[46:47], v[110:111]
	v_pk_fma_f32 v[112:113], v[118:119], v[62:63], v[112:113]
	v_pk_mul_f32 v[122:123], v[70:71], v[84:85] op_sel_hi:[0,1]
	ds_read_b128 v[22:25], v94 offset:24032
	v_pk_fma_f32 v[110:111], v[120:121], v[48:49], v[110:111]
	v_pk_fma_f32 v[112:113], v[120:121], v[64:65], v[112:113]
	v_pk_mul_f32 v[124:125], v[70:71], v[86:87] op_sel_hi:[0,1]
	ds_read_b128 v[18:21], v94 offset:24048
	v_pk_fma_f32 v[110:111], v[122:123], v[42:43], v[110:111]
	v_pk_fma_f32 v[112:113], v[122:123], v[58:59], v[112:113]
	v_pk_mul_f32 v[126:127], v[70:71], v[88:89] op_sel_hi:[0,1]
	ds_read_b128 v[2:5], v94 offset:24256
	v_pk_fma_f32 v[110:111], v[124:125], v[44:45], v[110:111]
	v_pk_fma_f32 v[112:113], v[124:125], v[60:61], v[112:113]
	v_pk_mul_f32 v[128:129], v[70:71], v[90:91] op_sel_hi:[0,1]
	ds_read_b128 v[6:9], v94 offset:24272
	v_pk_fma_f32 v[110:111], v[126:127], v[38:39], v[110:111]
	v_pk_fma_f32 v[112:113], v[126:127], v[54:55], v[112:113]
	ds_read_b128 v[14:17], v94 offset:24288
	v_pk_fma_f32 v[110:111], v[128:129], v[40:41], v[110:111]
	v_pk_fma_f32 v[112:113], v[128:129], v[56:57], v[112:113]
	ds_read_b128 v[10:13], v94 offset:24304
	v_add_f32_e32 v134, v110, v111
	v_add_f32_e32 v135, v112, v113
	ds_read_b32 v73, v95 offset:24512
	v_add_f32_dpp v134, v134, v134 quad_perm:[1,0,3,2] row_mask:0xf bank_mask:0xf bound_ctrl:1
	v_add_f32_dpp v135, v135, v135 quad_perm:[1,0,3,2] row_mask:0xf bank_mask:0xf bound_ctrl:1
	ds_read_b96 v[34:36], v1 offset:24768
	v_add_f32_dpp v134, v134, v134 quad_perm:[2,3,0,1] row_mask:0xf bank_mask:0xf bound_ctrl:1
	v_add_f32_dpp v135, v135, v135 quad_perm:[2,3,0,1] row_mask:0xf bank_mask:0xf bound_ctrl:1
	v_sub_f32_e32 v134, v0, v134
	v_mul_f32_e32 v134, v71, v134
	v_fma_f32 v135, v72, v134, v135
	v_cvt_pk_bf16_f32 v133, v135, v135
	v_pk_fma_f32 v[74:75], v[50:51], v[134:135], v[114:115] op_sel_hi:[1,0,1]
	v_pk_fma_f32 v[78:79], v[52:53], v[134:135], v[116:117] op_sel_hi:[1,0,1]
	global_store_short v157, v133, s[100:101]
	v_pk_fma_f32 v[80:81], v[46:47], v[134:135], v[118:119] op_sel_hi:[1,0,1]
	v_pk_fma_f32 v[82:83], v[48:49], v[134:135], v[120:121] op_sel_hi:[1,0,1]
	v_pk_fma_f32 v[84:85], v[42:43], v[134:135], v[122:123] op_sel_hi:[1,0,1]
	v_pk_fma_f32 v[86:87], v[44:45], v[134:135], v[124:125] op_sel_hi:[1,0,1]
	v_pk_fma_f32 v[88:89], v[38:39], v[134:135], v[126:127] op_sel_hi:[1,0,1]
	v_pk_fma_f32 v[90:91], v[40:41], v[134:135], v[128:129] op_sel_hi:[1,0,1]
	s_waitcnt lgkmcnt(0)
	v_pk_mul_f32 v[114:115], v[34:35], v[74:75] op_sel_hi:[0,1]
	v_pk_mul_f32 v[116:117], v[34:35], v[78:79] op_sel_hi:[0,1]
	v_pk_fma_f32 v[106:107], v[114:115], v[2:3], 0 op_sel_hi:[1,1,0]
	v_pk_fma_f32 v[108:109], v[114:115], v[30:31], 0 op_sel_hi:[1,1,0]
	v_pk_mul_f32 v[118:119], v[34:35], v[80:81] op_sel_hi:[0,1]
	ds_read_b128 v[66:69], v94 offset:24800
	v_pk_fma_f32 v[106:107], v[116:117], v[4:5], v[106:107]
	v_pk_fma_f32 v[108:109], v[116:117], v[32:33], v[108:109]
	v_pk_mul_f32 v[120:121], v[34:35], v[82:83] op_sel_hi:[0,1]
	ds_read_b128 v[62:65], v94 offset:24816
	v_pk_fma_f32 v[106:107], v[118:119], v[6:7], v[106:107]
	v_pk_fma_f32 v[108:109], v[118:119], v[26:27], v[108:109]
	v_pk_mul_f32 v[122:123], v[34:35], v[84:85] op_sel_hi:[0,1]
	ds_read_b128 v[58:61], v94 offset:24832
	v_pk_fma_f32 v[106:107], v[120:121], v[8:9], v[106:107]
	v_pk_fma_f32 v[108:109], v[120:121], v[28:29], v[108:109]
	v_pk_mul_f32 v[124:125], v[34:35], v[86:87] op_sel_hi:[0,1]
	ds_read_b128 v[54:57], v94 offset:24848
	v_pk_fma_f32 v[106:107], v[122:123], v[14:15], v[106:107]
	v_pk_fma_f32 v[108:109], v[122:123], v[22:23], v[108:109]
	v_pk_mul_f32 v[126:127], v[34:35], v[88:89] op_sel_hi:[0,1]
	ds_read_b128 v[50:53], v94 offset:25056
	v_pk_fma_f32 v[106:107], v[124:125], v[16:17], v[106:107]
	v_pk_fma_f32 v[108:109], v[124:125], v[24:25], v[108:109]
	v_pk_mul_f32 v[128:129], v[34:35], v[90:91] op_sel_hi:[0,1]
	ds_read_b128 v[46:49], v94 offset:25072
	v_pk_fma_f32 v[106:107], v[126:127], v[10:11], v[106:107]
	v_pk_fma_f32 v[108:109], v[126:127], v[18:19], v[108:109]
	ds_read_b128 v[42:45], v94 offset:25088
	v_pk_fma_f32 v[106:107], v[128:129], v[12:13], v[106:107]
	v_pk_fma_f32 v[108:109], v[128:129], v[20:21], v[108:109]
	ds_read_b128 v[38:41], v94 offset:25104
	v_add_f32_e32 v130, v106, v107
	v_add_f32_e32 v131, v108, v109
	ds_read_b32 v0, v95 offset:25312
	v_add_f32_dpp v130, v130, v130 quad_perm:[1,0,3,2] row_mask:0xf bank_mask:0xf bound_ctrl:1
	v_add_f32_dpp v131, v131, v131 quad_perm:[1,0,3,2] row_mask:0xf bank_mask:0xf bound_ctrl:1
	ds_read_b96 v[70:72], v1 offset:25568
	v_add_f32_dpp v130, v130, v130 quad_perm:[2,3,0,1] row_mask:0xf bank_mask:0xf bound_ctrl:1
	v_add_f32_dpp v131, v131, v131 quad_perm:[2,3,0,1] row_mask:0xf bank_mask:0xf bound_ctrl:1
	v_sub_f32_e32 v130, v73, v130
	v_mul_f32_e32 v130, v35, v130
	v_fma_f32 v131, v36, v130, v131
	v_cvt_pk_bf16_f32 v132, v131, v131
	v_pk_fma_f32 v[74:75], v[2:3], v[130:131], v[114:115] op_sel_hi:[1,0,1]
	v_pk_fma_f32 v[78:79], v[4:5], v[130:131], v[116:117] op_sel_hi:[1,0,1]
	global_store_short v158, v132, s[100:101]
	v_pk_fma_f32 v[80:81], v[6:7], v[130:131], v[118:119] op_sel_hi:[1,0,1]
	v_pk_fma_f32 v[82:83], v[8:9], v[130:131], v[120:121] op_sel_hi:[1,0,1]
	v_pk_fma_f32 v[84:85], v[14:15], v[130:131], v[122:123] op_sel_hi:[1,0,1]
	v_pk_fma_f32 v[86:87], v[16:17], v[130:131], v[124:125] op_sel_hi:[1,0,1]
	v_pk_fma_f32 v[88:89], v[10:11], v[130:131], v[126:127] op_sel_hi:[1,0,1]
	v_pk_fma_f32 v[90:91], v[12:13], v[130:131], v[128:129] op_sel_hi:[1,0,1]
	s_waitcnt lgkmcnt(0)
	v_pk_mul_f32 v[114:115], v[70:71], v[74:75] op_sel_hi:[0,1]
	v_pk_mul_f32 v[116:117], v[70:71], v[78:79] op_sel_hi:[0,1]
	v_pk_fma_f32 v[110:111], v[114:115], v[50:51], 0 op_sel_hi:[1,1,0]
	v_pk_fma_f32 v[112:113], v[114:115], v[66:67], 0 op_sel_hi:[1,1,0]
	v_pk_mul_f32 v[118:119], v[70:71], v[80:81] op_sel_hi:[0,1]
	v_pk_fma_f32 v[110:111], v[116:117], v[52:53], v[110:111]
	v_pk_fma_f32 v[112:113], v[116:117], v[68:69], v[112:113]
	v_pk_mul_f32 v[120:121], v[70:71], v[82:83] op_sel_hi:[0,1]
	v_pk_fma_f32 v[110:111], v[118:119], v[46:47], v[110:111]
	v_pk_fma_f32 v[112:113], v[118:119], v[62:63], v[112:113]
	v_pk_mul_f32 v[122:123], v[70:71], v[84:85] op_sel_hi:[0,1]
	v_pk_fma_f32 v[110:111], v[120:121], v[48:49], v[110:111]
	v_pk_fma_f32 v[112:113], v[120:121], v[64:65], v[112:113]
	v_pk_mul_f32 v[124:125], v[70:71], v[86:87] op_sel_hi:[0,1]
	v_pk_fma_f32 v[110:111], v[122:123], v[42:43], v[110:111]
	v_pk_fma_f32 v[112:113], v[122:123], v[58:59], v[112:113]
	v_pk_mul_f32 v[126:127], v[70:71], v[88:89] op_sel_hi:[0,1]
	v_pk_fma_f32 v[110:111], v[124:125], v[44:45], v[110:111]
	v_pk_fma_f32 v[112:113], v[124:125], v[60:61], v[112:113]
	v_pk_mul_f32 v[128:129], v[70:71], v[90:91] op_sel_hi:[0,1]
	v_pk_fma_f32 v[110:111], v[126:127], v[38:39], v[110:111]
	v_pk_fma_f32 v[112:113], v[126:127], v[54:55], v[112:113]
	v_pk_fma_f32 v[110:111], v[128:129], v[40:41], v[110:111]
	v_pk_fma_f32 v[112:113], v[128:129], v[56:57], v[112:113]
	v_add_f32_e32 v134, v110, v111
	v_add_f32_e32 v135, v112, v113
	s_nop 0
	v_add_f32_dpp v134, v134, v134 quad_perm:[1,0,3,2] row_mask:0xf bank_mask:0xf bound_ctrl:1
	v_add_f32_dpp v135, v135, v135 quad_perm:[1,0,3,2] row_mask:0xf bank_mask:0xf bound_ctrl:1
	s_nop 0
	v_add_f32_dpp v134, v134, v134 quad_perm:[2,3,0,1] row_mask:0xf bank_mask:0xf bound_ctrl:1
	v_add_f32_dpp v135, v135, v135 quad_perm:[2,3,0,1] row_mask:0xf bank_mask:0xf bound_ctrl:1
	v_sub_f32_e32 v134, v0, v134
	v_mul_f32_e32 v134, v71, v134
	v_fma_f32 v135, v72, v134, v135
	v_cvt_pk_bf16_f32 v133, v135, v135
	v_pk_fma_f32 v[74:75], v[50:51], v[134:135], v[114:115] op_sel_hi:[1,0,1]
	v_pk_fma_f32 v[78:79], v[52:53], v[134:135], v[116:117] op_sel_hi:[1,0,1]
	global_store_short v159, v133, s[100:101]
	v_pk_fma_f32 v[80:81], v[46:47], v[134:135], v[118:119] op_sel_hi:[1,0,1]
	v_pk_fma_f32 v[82:83], v[48:49], v[134:135], v[120:121] op_sel_hi:[1,0,1]
	v_pk_fma_f32 v[84:85], v[42:43], v[134:135], v[122:123] op_sel_hi:[1,0,1]
	v_pk_fma_f32 v[86:87], v[44:45], v[134:135], v[124:125] op_sel_hi:[1,0,1]
	v_pk_fma_f32 v[88:89], v[38:39], v[134:135], v[126:127] op_sel_hi:[1,0,1]
	v_pk_fma_f32 v[90:91], v[40:41], v[134:135], v[128:129] op_sel_hi:[1,0,1]
	s_branch .LBB0_899
